# GEMM K-loops: ds_reads issued first in every load segment (loop-head SALU, DMA address setup moved behind them), loop-end counter updates moved in front of the closing barrier
# speedup vs baseline: 1.0080x; 1.0080x over previous
.LBB0_72:
	s_add_i32 s45, 0, 0x10000
	v_add_u32_e32 v138, s45, v141
	s_add_i32 s48, 0, 0x14000
	ds_read_b128 v[144:147], v138
	ds_read_b128 v[148:151], v138 offset:1024
	ds_read_b128 v[152:155], v138 offset:2048
	ds_read_b128 v[156:159], v138 offset:3072
	v_add_u32_e32 v138, s48, v141
	ds_read_b128 v[170:173], v138
	ds_read_b128 v[174:177], v138 offset:1024
	ds_read_b128 v[178:181], v138 offset:2048
	ds_read_b128 v[182:185], v138 offset:3072
	v_lshl_add_u64 v[138:139], s[20:21], 0, v[136:137]
	s_add_i32 m0, s29, 0xc000
	ds_read_b128 v[186:189], v143
	ds_read_b128 v[190:193], v143 offset:1024
	ds_read_b128 v[194:197], v143 offset:2048
	ds_read_b128 v[198:201], v143 offset:3072
	ds_read_b128 v[202:205], v143 offset:4096
	ds_read_b128 v[228:231], v143 offset:5120
	ds_read_b128 v[232:235], v143 offset:6144
	ds_read_b128 v[236:239], v143 offset:7168
	s_add_u32 s22, s20, 0xfffc0080
	s_addc_u32 s23, s21, -1
	s_cmp_eq_u32 s44, 12
	s_cselect_b32 s25, s15, s23
	s_cselect_b32 s24, s40, s22
	s_cselect_b32 s23, s13, s43
	s_cselect_b32 s22, s41, s42
	global_load_lds_dwordx4 v[138:139], off
	v_lshl_add_u64 v[138:139], s[20:21], 0, v[134:135]
	s_add_i32 m0, s29, 0xe000
	s_nop 0
	global_load_lds_dwordx4 v[138:139], off
	s_waitcnt vmcnt(8)
	s_waitcnt lgkmcnt(0)
	s_barrier
	s_setprio 1
	s_waitcnt lgkmcnt(0)
	v_mfma_f32_16x16x32_bf16 v[124:127], v[144:147], v[186:189], v[124:127]
	v_mfma_f32_16x16x32_bf16 v[120:123], v[152:155], v[186:189], v[120:123]
	v_mfma_f32_16x16x32_bf16 v[108:111], v[144:147], v[194:197], v[108:111]
	v_mfma_f32_16x16x32_bf16 v[104:107], v[152:155], v[194:197], v[104:107]
	v_mfma_f32_16x16x32_bf16 v[92:95], v[144:147], v[202:205], v[92:95]
	v_mfma_f32_16x16x32_bf16 v[88:91], v[152:155], v[202:205], v[88:91]
	v_mfma_f32_16x16x32_bf16 v[76:79], v[144:147], v[232:235], v[76:79]
	v_mfma_f32_16x16x32_bf16 v[72:75], v[152:155], v[232:235], v[72:75]
	v_mfma_f32_16x16x32_bf16 v[124:127], v[148:151], v[190:193], v[124:127]
	v_mfma_f32_16x16x32_bf16 v[120:123], v[156:159], v[190:193], v[120:123]
	v_mfma_f32_16x16x32_bf16 v[108:111], v[148:151], v[198:201], v[108:111]
	v_mfma_f32_16x16x32_bf16 v[104:107], v[156:159], v[198:201], v[104:107]
	v_mfma_f32_16x16x32_bf16 v[92:95], v[148:151], v[228:231], v[92:95]
	v_mfma_f32_16x16x32_bf16 v[88:91], v[156:159], v[228:231], v[88:91]
	v_mfma_f32_16x16x32_bf16 v[76:79], v[148:151], v[236:239], v[76:79]
	v_mfma_f32_16x16x32_bf16 v[72:75], v[156:159], v[236:239], v[72:75]
	s_setprio 0
	s_setprio 1
	v_mfma_f32_16x16x32_bf16 v[116:119], v[170:173], v[186:189], v[116:119]
	v_mfma_f32_16x16x32_bf16 v[112:115], v[178:181], v[186:189], v[112:115]
	v_mfma_f32_16x16x32_bf16 v[100:103], v[170:173], v[194:197], v[100:103]
	v_mfma_f32_16x16x32_bf16 v[96:99], v[178:181], v[194:197], v[96:99]
	v_mfma_f32_16x16x32_bf16 v[84:87], v[170:173], v[202:205], v[84:87]
	v_mfma_f32_16x16x32_bf16 v[80:83], v[178:181], v[202:205], v[80:83]
	v_mfma_f32_16x16x32_bf16 v[68:71], v[170:173], v[232:235], v[68:71]
	v_mfma_f32_16x16x32_bf16 v[64:67], v[178:181], v[232:235], v[64:67]
	v_mfma_f32_16x16x32_bf16 v[116:119], v[174:177], v[190:193], v[116:119]
	v_mfma_f32_16x16x32_bf16 v[112:115], v[182:185], v[190:193], v[112:115]
	v_mfma_f32_16x16x32_bf16 v[100:103], v[174:177], v[198:201], v[100:103]
	v_mfma_f32_16x16x32_bf16 v[96:99], v[182:185], v[198:201], v[96:99]
	v_mfma_f32_16x16x32_bf16 v[84:87], v[174:177], v[228:231], v[84:87]
	v_mfma_f32_16x16x32_bf16 v[80:83], v[182:185], v[228:231], v[80:83]
	v_mfma_f32_16x16x32_bf16 v[68:71], v[174:177], v[236:239], v[68:71]
	v_mfma_f32_16x16x32_bf16 v[64:67], v[182:185], v[236:239], v[64:67]
	s_setprio 0
	s_barrier
	ds_read_b128 v[186:189], v143 offset:16384
	ds_read_b128 v[190:193], v143 offset:17408
	ds_read_b128 v[194:197], v143 offset:18432
	ds_read_b128 v[198:201], v143 offset:19456
	ds_read_b128 v[202:205], v143 offset:20480
	ds_read_b128 v[228:231], v143 offset:21504
	ds_read_b128 v[232:235], v143 offset:22528
	ds_read_b128 v[236:239], v143 offset:23552
	s_add_i32 s45, s45, s77
	s_mov_b32 m0, s45
	v_lshl_add_u64 v[138:139], s[22:23], 0, v[160:161]
	global_load_lds_dwordx4 v[138:139], off
	s_add_i32 m0, s45, 0x2000
	s_add_u32 s46, s22, 0x40000
	v_lshl_add_u64 v[166:167], s[22:23], 0, v[128:129]
	s_addc_u32 s47, s23, 0
	s_add_i32 s45, s48, s77
	global_load_lds_dwordx4 v[166:167], off
	v_lshl_add_u64 v[168:169], s[46:47], 0, v[160:161]
	s_mov_b32 m0, s45
	v_lshl_add_u64 v[206:207], s[24:25], 0, v[130:131]
	global_load_lds_dwordx4 v[168:169], off
	v_lshl_add_u64 v[168:169], s[46:47], 0, v[128:129]
	s_add_i32 m0, s45, 0x2000
	s_nop 0
	global_load_lds_dwordx4 v[168:169], off
	v_lshl_add_u64 v[168:169], s[24:25], 0, v[132:133]
	s_mov_b32 m0, s29
	s_nop 0
	global_load_lds_dwordx4 v[168:169], off
	s_mov_b32 m0, s30
	s_nop 0
	global_load_lds_dwordx4 v[206:207], off
	s_waitcnt vmcnt(8)
	s_waitcnt lgkmcnt(0)
	s_barrier
	s_setprio 1
	s_waitcnt lgkmcnt(0)
	v_mfma_f32_16x16x32_bf16 v[60:63], v[144:147], v[186:189], v[60:63]
	v_mfma_f32_16x16x32_bf16 v[56:59], v[152:155], v[186:189], v[56:59]
	v_mfma_f32_16x16x32_bf16 v[44:47], v[144:147], v[194:197], v[44:47]
	v_mfma_f32_16x16x32_bf16 v[40:43], v[152:155], v[194:197], v[40:43]
	v_mfma_f32_16x16x32_bf16 v[28:31], v[144:147], v[202:205], v[28:31]
	v_mfma_f32_16x16x32_bf16 v[24:27], v[152:155], v[202:205], v[24:27]
	v_mfma_f32_16x16x32_bf16 v[12:15], v[144:147], v[232:235], v[12:15]
	v_mfma_f32_16x16x32_bf16 v[8:11], v[152:155], v[232:235], v[8:11]
	v_mfma_f32_16x16x32_bf16 v[60:63], v[148:151], v[190:193], v[60:63]
	v_mfma_f32_16x16x32_bf16 v[56:59], v[156:159], v[190:193], v[56:59]
	v_mfma_f32_16x16x32_bf16 v[44:47], v[148:151], v[198:201], v[44:47]
	v_mfma_f32_16x16x32_bf16 v[40:43], v[156:159], v[198:201], v[40:43]
	v_mfma_f32_16x16x32_bf16 v[28:31], v[148:151], v[228:231], v[28:31]
	v_mfma_f32_16x16x32_bf16 v[24:27], v[156:159], v[228:231], v[24:27]
	v_mfma_f32_16x16x32_bf16 v[12:15], v[148:151], v[236:239], v[12:15]
	v_mfma_f32_16x16x32_bf16 v[8:11], v[156:159], v[236:239], v[8:11]
	s_setprio 0
	s_setprio 1
	v_mfma_f32_16x16x32_bf16 v[52:55], v[170:173], v[186:189], v[52:55]
	v_mfma_f32_16x16x32_bf16 v[48:51], v[178:181], v[186:189], v[48:51]
	v_mfma_f32_16x16x32_bf16 v[36:39], v[170:173], v[194:197], v[36:39]
	v_mfma_f32_16x16x32_bf16 v[32:35], v[178:181], v[194:197], v[32:35]
	v_mfma_f32_16x16x32_bf16 v[20:23], v[170:173], v[202:205], v[20:23]
	v_mfma_f32_16x16x32_bf16 v[16:19], v[178:181], v[202:205], v[16:19]
	v_mfma_f32_16x16x32_bf16 v[4:7], v[170:173], v[232:235], v[4:7]
	v_mfma_f32_16x16x32_bf16 v[0:3], v[178:181], v[232:235], v[0:3]
	v_mfma_f32_16x16x32_bf16 v[52:55], v[174:177], v[190:193], v[52:55]
	v_mfma_f32_16x16x32_bf16 v[48:51], v[182:185], v[190:193], v[48:51]
	v_mfma_f32_16x16x32_bf16 v[36:39], v[174:177], v[198:201], v[36:39]
	v_mfma_f32_16x16x32_bf16 v[32:35], v[182:185], v[198:201], v[32:35]
	v_mfma_f32_16x16x32_bf16 v[20:23], v[174:177], v[228:231], v[20:23]
	v_mfma_f32_16x16x32_bf16 v[16:19], v[182:185], v[228:231], v[16:19]
	v_mfma_f32_16x16x32_bf16 v[4:7], v[174:177], v[236:239], v[4:7]
	v_mfma_f32_16x16x32_bf16 v[0:3], v[182:185], v[236:239], v[0:3]
	s_setprio 0
	s_barrier
	s_add_i32 s45, 0, 0x18000
	s_add_i32 s46, 0, 0x1c000
	v_add_u32_e32 v156, s45, v141
	v_add_u32_e32 v182, s46, v141
	ds_read_b128 v[144:147], v156
	ds_read_b128 v[148:151], v156 offset:1024
	ds_read_b128 v[152:155], v156 offset:2048
	ds_read_b128 v[156:159], v156 offset:3072
	ds_read_b128 v[170:173], v182
	ds_read_b128 v[174:177], v182 offset:1024
	ds_read_b128 v[178:181], v182 offset:2048
	ds_read_b128 v[182:185], v182 offset:3072
	s_add_u32 s24, s24, 0x40000
	s_addc_u32 s25, s25, 0
	s_mov_b32 m0, s31
	v_lshl_add_u64 v[240:241], s[24:25], 0, v[132:133]
	ds_read_b128 v[186:189], v143 offset:32768
	ds_read_b128 v[190:193], v143 offset:33792
	ds_read_b128 v[194:197], v143 offset:34816
	ds_read_b128 v[198:201], v143 offset:35840
	ds_read_b128 v[202:205], v143 offset:36864
	ds_read_b128 v[228:231], v143 offset:37888
	ds_read_b128 v[232:235], v143 offset:38912
	ds_read_b128 v[236:239], v143 offset:39936
	global_load_lds_dwordx4 v[240:241], off
	v_lshl_add_u64 v[240:241], s[24:25], 0, v[130:131]
	s_mov_b32 m0, s34
	s_nop 0
	global_load_lds_dwordx4 v[240:241], off
	s_waitcnt vmcnt(8)
	s_waitcnt lgkmcnt(0)
	s_barrier
	s_setprio 1
	s_waitcnt lgkmcnt(0)
	v_mfma_f32_16x16x32_bf16 v[124:127], v[144:147], v[186:189], v[124:127]
	v_mfma_f32_16x16x32_bf16 v[120:123], v[152:155], v[186:189], v[120:123]
	v_mfma_f32_16x16x32_bf16 v[108:111], v[144:147], v[194:197], v[108:111]
	v_mfma_f32_16x16x32_bf16 v[104:107], v[152:155], v[194:197], v[104:107]
	v_mfma_f32_16x16x32_bf16 v[92:95], v[144:147], v[202:205], v[92:95]
	v_mfma_f32_16x16x32_bf16 v[88:91], v[152:155], v[202:205], v[88:91]
	v_mfma_f32_16x16x32_bf16 v[76:79], v[144:147], v[232:235], v[76:79]
	v_mfma_f32_16x16x32_bf16 v[72:75], v[152:155], v[232:235], v[72:75]
	v_mfma_f32_16x16x32_bf16 v[124:127], v[148:151], v[190:193], v[124:127]
	v_mfma_f32_16x16x32_bf16 v[120:123], v[156:159], v[190:193], v[120:123]
	v_mfma_f32_16x16x32_bf16 v[108:111], v[148:151], v[198:201], v[108:111]
	v_mfma_f32_16x16x32_bf16 v[104:107], v[156:159], v[198:201], v[104:107]
	v_mfma_f32_16x16x32_bf16 v[92:95], v[148:151], v[228:231], v[92:95]
	v_mfma_f32_16x16x32_bf16 v[88:91], v[156:159], v[228:231], v[88:91]
	v_mfma_f32_16x16x32_bf16 v[76:79], v[148:151], v[236:239], v[76:79]
	v_mfma_f32_16x16x32_bf16 v[72:75], v[156:159], v[236:239], v[72:75]
	s_setprio 0
	s_setprio 1
	v_mfma_f32_16x16x32_bf16 v[116:119], v[170:173], v[186:189], v[116:119]
	v_mfma_f32_16x16x32_bf16 v[112:115], v[178:181], v[186:189], v[112:115]
	v_mfma_f32_16x16x32_bf16 v[100:103], v[170:173], v[194:197], v[100:103]
	v_mfma_f32_16x16x32_bf16 v[96:99], v[178:181], v[194:197], v[96:99]
	v_mfma_f32_16x16x32_bf16 v[84:87], v[170:173], v[202:205], v[84:87]
	v_mfma_f32_16x16x32_bf16 v[80:83], v[178:181], v[202:205], v[80:83]
	v_mfma_f32_16x16x32_bf16 v[68:71], v[170:173], v[232:235], v[68:71]
	v_mfma_f32_16x16x32_bf16 v[64:67], v[178:181], v[232:235], v[64:67]
	v_mfma_f32_16x16x32_bf16 v[116:119], v[174:177], v[190:193], v[116:119]
	v_mfma_f32_16x16x32_bf16 v[112:115], v[182:185], v[190:193], v[112:115]
	v_mfma_f32_16x16x32_bf16 v[100:103], v[174:177], v[198:201], v[100:103]
	v_mfma_f32_16x16x32_bf16 v[96:99], v[182:185], v[198:201], v[96:99]
	v_mfma_f32_16x16x32_bf16 v[84:87], v[174:177], v[228:231], v[84:87]
	v_mfma_f32_16x16x32_bf16 v[80:83], v[182:185], v[228:231], v[80:83]
	v_mfma_f32_16x16x32_bf16 v[68:71], v[174:177], v[236:239], v[68:71]
	v_mfma_f32_16x16x32_bf16 v[64:67], v[182:185], v[236:239], v[64:67]
	s_setprio 0
	s_barrier
	ds_read_b128 v[186:189], v143 offset:49152
	ds_read_b128 v[190:193], v143 offset:50176
	ds_read_b128 v[194:197], v143 offset:51200
	ds_read_b128 v[198:201], v143 offset:52224
	ds_read_b128 v[202:205], v143 offset:53248
	ds_read_b128 v[228:231], v143 offset:54272
	ds_read_b128 v[232:235], v143 offset:55296
	ds_read_b128 v[236:239], v143 offset:56320
	s_add_i32 s24, s45, s77
	s_mov_b32 m0, s24
	v_lshl_add_u64 v[138:139], v[138:139], 0, s[96:97]
	global_load_lds_dwordx4 v[138:139], off
	s_add_i32 m0, s24, 0x2000
	s_add_u32 s22, s22, 0x40080
	v_lshl_add_u64 v[138:139], v[166:167], 0, s[96:97]
	s_addc_u32 s23, s23, 0
	s_add_i32 s24, s46, s77
	global_load_lds_dwordx4 v[138:139], off
	v_lshl_add_u64 v[138:139], s[22:23], 0, v[160:161]
	s_mov_b32 m0, s24
	s_nop 0
	global_load_lds_dwordx4 v[138:139], off
	v_lshl_add_u64 v[138:139], s[22:23], 0, v[128:129]
	s_add_i32 m0, s24, 0x2000
	s_nop 0
	global_load_lds_dwordx4 v[138:139], off
	v_lshl_add_u64 v[138:139], v[168:169], 0, s[96:97]
	s_mov_b32 m0, s35
	s_nop 0
	global_load_lds_dwordx4 v[138:139], off
	v_lshl_add_u64 v[138:139], v[206:207], 0, s[96:97]
	s_mov_b32 m0, s36
	s_nop 0
	global_load_lds_dwordx4 v[138:139], off
	s_waitcnt vmcnt(8)
	s_waitcnt lgkmcnt(0)
	s_barrier
	s_setprio 1
	s_waitcnt lgkmcnt(0)
	v_mfma_f32_16x16x32_bf16 v[60:63], v[144:147], v[186:189], v[60:63]
	v_mfma_f32_16x16x32_bf16 v[56:59], v[152:155], v[186:189], v[56:59]
	v_mfma_f32_16x16x32_bf16 v[44:47], v[144:147], v[194:197], v[44:47]
	v_mfma_f32_16x16x32_bf16 v[40:43], v[152:155], v[194:197], v[40:43]
	v_mfma_f32_16x16x32_bf16 v[28:31], v[144:147], v[202:205], v[28:31]
	v_mfma_f32_16x16x32_bf16 v[24:27], v[152:155], v[202:205], v[24:27]
	v_mfma_f32_16x16x32_bf16 v[12:15], v[144:147], v[232:235], v[12:15]
	v_mfma_f32_16x16x32_bf16 v[8:11], v[152:155], v[232:235], v[8:11]
	v_mfma_f32_16x16x32_bf16 v[60:63], v[148:151], v[190:193], v[60:63]
	v_mfma_f32_16x16x32_bf16 v[56:59], v[156:159], v[190:193], v[56:59]
	v_mfma_f32_16x16x32_bf16 v[44:47], v[148:151], v[198:201], v[44:47]
	v_mfma_f32_16x16x32_bf16 v[40:43], v[156:159], v[198:201], v[40:43]
	v_mfma_f32_16x16x32_bf16 v[28:31], v[148:151], v[228:231], v[28:31]
	v_mfma_f32_16x16x32_bf16 v[24:27], v[156:159], v[228:231], v[24:27]
	v_mfma_f32_16x16x32_bf16 v[12:15], v[148:151], v[236:239], v[12:15]
	v_mfma_f32_16x16x32_bf16 v[8:11], v[156:159], v[236:239], v[8:11]
	s_setprio 0
	s_setprio 1
	v_mfma_f32_16x16x32_bf16 v[52:55], v[170:173], v[186:189], v[52:55]
	v_mfma_f32_16x16x32_bf16 v[48:51], v[178:181], v[186:189], v[48:51]
	v_mfma_f32_16x16x32_bf16 v[36:39], v[170:173], v[194:197], v[36:39]
	v_mfma_f32_16x16x32_bf16 v[32:35], v[178:181], v[194:197], v[32:35]
	v_mfma_f32_16x16x32_bf16 v[20:23], v[170:173], v[202:205], v[20:23]
	v_mfma_f32_16x16x32_bf16 v[16:19], v[178:181], v[202:205], v[16:19]
	v_mfma_f32_16x16x32_bf16 v[4:7], v[170:173], v[232:235], v[4:7]
	v_mfma_f32_16x16x32_bf16 v[0:3], v[178:181], v[232:235], v[0:3]
	v_mfma_f32_16x16x32_bf16 v[52:55], v[174:177], v[190:193], v[52:55]
	v_mfma_f32_16x16x32_bf16 v[48:51], v[182:185], v[190:193], v[48:51]
	v_mfma_f32_16x16x32_bf16 v[36:39], v[174:177], v[198:201], v[36:39]
	v_mfma_f32_16x16x32_bf16 v[32:35], v[182:185], v[198:201], v[32:35]
	v_mfma_f32_16x16x32_bf16 v[20:23], v[174:177], v[228:231], v[20:23]
	v_mfma_f32_16x16x32_bf16 v[16:19], v[182:185], v[228:231], v[16:19]
	v_mfma_f32_16x16x32_bf16 v[4:7], v[174:177], v[236:239], v[4:7]
	v_mfma_f32_16x16x32_bf16 v[0:3], v[182:185], v[236:239], v[0:3]
	s_setprio 0
	s_add_i32 s44, s44, 2
	s_add_u32 s42, s42, 0x100
	s_addc_u32 s43, s43, 0
	s_add_u32 s20, s20, 0x100
	s_addc_u32 s21, s21, 0
	s_cmp_gt_u32 s44, 13
	s_barrier
	s_cbranch_scc0 .LBB0_72
	v_readlane_b32 s20, v253, 23
	v_readlane_b32 s21, v253, 24
	s_and_b64 vcc, exec, s[20:21]
	s_cbranch_vccz .LBB0_75
	s_barrier

.LBB0_105:
	s_add_i32 s45, 0, 0x10000
	s_add_i32 s48, 0, 0x14000
	v_add_u32_e32 v150, s45, v157
	v_add_u32_e32 v154, s48, v157
	ds_read_b128 v[128:131], v150
	ds_read_b128 v[132:135], v150 offset:1024
	ds_read_b128 v[146:149], v150 offset:2048
	ds_read_b128 v[150:153], v150 offset:3072
	ds_read_b128 v[170:173], v154
	ds_read_b128 v[174:177], v154 offset:1024
	ds_read_b128 v[178:181], v154 offset:2048
	ds_read_b128 v[182:185], v154 offset:3072
	v_lshl_add_u64 v[154:155], s[18:19], 0, v[144:145]
	s_add_i32 m0, s27, 0xc000
	ds_read_b128 v[186:189], v159
	ds_read_b128 v[190:193], v159 offset:1024
	ds_read_b128 v[194:197], v159 offset:2048
	ds_read_b128 v[198:201], v159 offset:3072
	ds_read_b128 v[202:205], v159 offset:4096
	ds_read_b128 v[228:231], v159 offset:5120
	ds_read_b128 v[232:235], v159 offset:6144
	ds_read_b128 v[236:239], v159 offset:7168
	s_add_u32 s20, s18, 0xfffc0080
	s_addc_u32 s21, s19, -1
	s_cmp_eq_u32 s44, 12
	s_cselect_b32 s23, s13, s21
	s_cselect_b32 s22, s40, s20
	s_cselect_b32 s21, s11, s43
	s_cselect_b32 s20, s41, s42
	global_load_lds_dwordx4 v[154:155], off
	v_lshl_add_u64 v[154:155], s[18:19], 0, v[142:143]
	s_add_i32 m0, s27, 0xe000
	s_nop 0
	global_load_lds_dwordx4 v[154:155], off
	s_waitcnt vmcnt(8)
	s_waitcnt lgkmcnt(0)
	s_barrier
	s_setprio 1
	s_waitcnt lgkmcnt(0)
	v_mfma_f32_16x16x32_bf16 v[124:127], v[128:131], v[186:189], v[124:127]
	v_mfma_f32_16x16x32_bf16 v[120:123], v[146:149], v[186:189], v[120:123]
	v_mfma_f32_16x16x32_bf16 v[116:119], v[128:131], v[194:197], v[116:119]
	v_mfma_f32_16x16x32_bf16 v[112:115], v[146:149], v[194:197], v[112:115]
	v_mfma_f32_16x16x32_bf16 v[108:111], v[128:131], v[202:205], v[108:111]
	v_mfma_f32_16x16x32_bf16 v[104:107], v[146:149], v[202:205], v[104:107]
	v_mfma_f32_16x16x32_bf16 v[100:103], v[128:131], v[232:235], v[100:103]
	v_mfma_f32_16x16x32_bf16 v[96:99], v[146:149], v[232:235], v[96:99]
	v_mfma_f32_16x16x32_bf16 v[124:127], v[132:135], v[190:193], v[124:127]
	v_mfma_f32_16x16x32_bf16 v[120:123], v[150:153], v[190:193], v[120:123]
	v_mfma_f32_16x16x32_bf16 v[116:119], v[132:135], v[198:201], v[116:119]
	v_mfma_f32_16x16x32_bf16 v[112:115], v[150:153], v[198:201], v[112:115]
	v_mfma_f32_16x16x32_bf16 v[108:111], v[132:135], v[228:231], v[108:111]
	v_mfma_f32_16x16x32_bf16 v[104:107], v[150:153], v[228:231], v[104:107]
	v_mfma_f32_16x16x32_bf16 v[100:103], v[132:135], v[236:239], v[100:103]
	v_mfma_f32_16x16x32_bf16 v[96:99], v[150:153], v[236:239], v[96:99]
	s_setprio 0
	s_setprio 1
	v_mfma_f32_16x16x32_bf16 v[64:67], v[170:173], v[186:189], v[64:67]
	v_mfma_f32_16x16x32_bf16 v[60:63], v[178:181], v[186:189], v[60:63]
	v_mfma_f32_16x16x32_bf16 v[52:55], v[170:173], v[194:197], v[52:55]
	v_mfma_f32_16x16x32_bf16 v[48:51], v[178:181], v[194:197], v[48:51]
	v_mfma_f32_16x16x32_bf16 v[44:47], v[170:173], v[202:205], v[44:47]
	v_mfma_f32_16x16x32_bf16 v[40:43], v[178:181], v[202:205], v[40:43]
	v_mfma_f32_16x16x32_bf16 v[36:39], v[170:173], v[232:235], v[36:39]
	v_mfma_f32_16x16x32_bf16 v[32:35], v[178:181], v[232:235], v[32:35]
	v_mfma_f32_16x16x32_bf16 v[64:67], v[174:177], v[190:193], v[64:67]
	v_mfma_f32_16x16x32_bf16 v[60:63], v[182:185], v[190:193], v[60:63]
	v_mfma_f32_16x16x32_bf16 v[52:55], v[174:177], v[198:201], v[52:55]
	v_mfma_f32_16x16x32_bf16 v[48:51], v[182:185], v[198:201], v[48:51]
	v_mfma_f32_16x16x32_bf16 v[44:47], v[174:177], v[228:231], v[44:47]
	v_mfma_f32_16x16x32_bf16 v[40:43], v[182:185], v[228:231], v[40:43]
	v_mfma_f32_16x16x32_bf16 v[36:39], v[174:177], v[236:239], v[36:39]
	v_mfma_f32_16x16x32_bf16 v[32:35], v[182:185], v[236:239], v[32:35]
	s_setprio 0
	s_barrier
	ds_read_b128 v[186:189], v159 offset:16384
	ds_read_b128 v[190:193], v159 offset:17408
	ds_read_b128 v[194:197], v159 offset:18432
	ds_read_b128 v[198:201], v159 offset:19456
	ds_read_b128 v[202:205], v159 offset:20480
	ds_read_b128 v[228:231], v159 offset:21504
	ds_read_b128 v[232:235], v159 offset:22528
	ds_read_b128 v[236:239], v159 offset:23552
	s_add_i32 s45, s45, s77
	s_mov_b32 m0, s45
	v_lshl_add_u64 v[154:155], s[20:21], 0, v[160:161]
	global_load_lds_dwordx4 v[154:155], off
	s_add_i32 m0, s45, 0x2000
	s_add_u32 s46, s20, 0x40000
	v_lshl_add_u64 v[166:167], s[20:21], 0, v[136:137]
	s_addc_u32 s47, s21, 0
	s_add_i32 s45, s48, s77
	global_load_lds_dwordx4 v[166:167], off
	v_lshl_add_u64 v[168:169], s[46:47], 0, v[160:161]
	s_mov_b32 m0, s45
	v_lshl_add_u64 v[206:207], s[22:23], 0, v[138:139]
	global_load_lds_dwordx4 v[168:169], off
	v_lshl_add_u64 v[168:169], s[46:47], 0, v[136:137]
	s_add_i32 m0, s45, 0x2000
	s_nop 0
	global_load_lds_dwordx4 v[168:169], off
	v_lshl_add_u64 v[168:169], s[22:23], 0, v[140:141]
	s_mov_b32 m0, s27
	s_nop 0
	global_load_lds_dwordx4 v[168:169], off
	s_mov_b32 m0, s28
	s_nop 0
	global_load_lds_dwordx4 v[206:207], off
	s_waitcnt vmcnt(8)
	s_waitcnt lgkmcnt(0)
	s_barrier
	s_setprio 1
	s_waitcnt lgkmcnt(0)
	v_mfma_f32_16x16x32_bf16 v[92:95], v[128:131], v[186:189], v[92:95]
	v_mfma_f32_16x16x32_bf16 v[88:91], v[146:149], v[186:189], v[88:91]
	v_mfma_f32_16x16x32_bf16 v[84:87], v[128:131], v[194:197], v[84:87]
	v_mfma_f32_16x16x32_bf16 v[80:83], v[146:149], v[194:197], v[80:83]
	v_mfma_f32_16x16x32_bf16 v[76:79], v[128:131], v[202:205], v[76:79]
	v_mfma_f32_16x16x32_bf16 v[72:75], v[146:149], v[202:205], v[72:75]
	v_mfma_f32_16x16x32_bf16 v[68:71], v[128:131], v[232:235], v[68:71]
	v_mfma_f32_16x16x32_bf16 v[56:59], v[146:149], v[232:235], v[56:59]
	v_mfma_f32_16x16x32_bf16 v[92:95], v[132:135], v[190:193], v[92:95]
	v_mfma_f32_16x16x32_bf16 v[88:91], v[150:153], v[190:193], v[88:91]
	v_mfma_f32_16x16x32_bf16 v[84:87], v[132:135], v[198:201], v[84:87]
	v_mfma_f32_16x16x32_bf16 v[80:83], v[150:153], v[198:201], v[80:83]
	v_mfma_f32_16x16x32_bf16 v[76:79], v[132:135], v[228:231], v[76:79]
	v_mfma_f32_16x16x32_bf16 v[72:75], v[150:153], v[228:231], v[72:75]
	v_mfma_f32_16x16x32_bf16 v[68:71], v[132:135], v[236:239], v[68:71]
	v_mfma_f32_16x16x32_bf16 v[56:59], v[150:153], v[236:239], v[56:59]
	s_setprio 0
	s_setprio 1
	v_mfma_f32_16x16x32_bf16 v[28:31], v[170:173], v[186:189], v[28:31]
	v_mfma_f32_16x16x32_bf16 v[24:27], v[178:181], v[186:189], v[24:27]
	v_mfma_f32_16x16x32_bf16 v[20:23], v[170:173], v[194:197], v[20:23]
	v_mfma_f32_16x16x32_bf16 v[16:19], v[178:181], v[194:197], v[16:19]
	v_mfma_f32_16x16x32_bf16 v[12:15], v[170:173], v[202:205], v[12:15]
	v_mfma_f32_16x16x32_bf16 v[8:11], v[178:181], v[202:205], v[8:11]
	v_mfma_f32_16x16x32_bf16 v[4:7], v[170:173], v[232:235], v[4:7]
	v_mfma_f32_16x16x32_bf16 v[0:3], v[178:181], v[232:235], v[0:3]
	v_mfma_f32_16x16x32_bf16 v[28:31], v[174:177], v[190:193], v[28:31]
	v_mfma_f32_16x16x32_bf16 v[24:27], v[182:185], v[190:193], v[24:27]
	v_mfma_f32_16x16x32_bf16 v[20:23], v[174:177], v[198:201], v[20:23]
	v_mfma_f32_16x16x32_bf16 v[16:19], v[182:185], v[198:201], v[16:19]
	v_mfma_f32_16x16x32_bf16 v[12:15], v[174:177], v[228:231], v[12:15]
	v_mfma_f32_16x16x32_bf16 v[8:11], v[182:185], v[228:231], v[8:11]
	v_mfma_f32_16x16x32_bf16 v[4:7], v[174:177], v[236:239], v[4:7]
	v_mfma_f32_16x16x32_bf16 v[0:3], v[182:185], v[236:239], v[0:3]
	s_setprio 0
	s_barrier
	s_add_i32 s45, 0, 0x18000
	s_add_i32 s46, 0, 0x1c000
	v_add_u32_e32 v150, s45, v157
	v_add_u32_e32 v182, s46, v157
	ds_read_b128 v[128:131], v150
	ds_read_b128 v[132:135], v150 offset:1024
	ds_read_b128 v[146:149], v150 offset:2048
	ds_read_b128 v[150:153], v150 offset:3072
	ds_read_b128 v[170:173], v182
	ds_read_b128 v[174:177], v182 offset:1024
	ds_read_b128 v[178:181], v182 offset:2048
	ds_read_b128 v[182:185], v182 offset:3072
	s_add_u32 s22, s22, 0x40000
	s_addc_u32 s23, s23, 0
	s_mov_b32 m0, s29
	v_lshl_add_u64 v[240:241], s[22:23], 0, v[140:141]
	ds_read_b128 v[186:189], v159 offset:32768
	ds_read_b128 v[190:193], v159 offset:33792
	ds_read_b128 v[194:197], v159 offset:34816
	ds_read_b128 v[198:201], v159 offset:35840
	ds_read_b128 v[202:205], v159 offset:36864
	ds_read_b128 v[228:231], v159 offset:37888
	ds_read_b128 v[232:235], v159 offset:38912
	ds_read_b128 v[236:239], v159 offset:39936
	global_load_lds_dwordx4 v[240:241], off
	v_lshl_add_u64 v[240:241], s[22:23], 0, v[138:139]
	s_mov_b32 m0, s30
	s_nop 0
	global_load_lds_dwordx4 v[240:241], off
	s_waitcnt vmcnt(8)
	s_waitcnt lgkmcnt(0)
	s_barrier
	s_setprio 1
	s_waitcnt lgkmcnt(0)
	v_mfma_f32_16x16x32_bf16 v[124:127], v[128:131], v[186:189], v[124:127]
	v_mfma_f32_16x16x32_bf16 v[120:123], v[146:149], v[186:189], v[120:123]
	v_mfma_f32_16x16x32_bf16 v[116:119], v[128:131], v[194:197], v[116:119]
	v_mfma_f32_16x16x32_bf16 v[112:115], v[146:149], v[194:197], v[112:115]
	v_mfma_f32_16x16x32_bf16 v[108:111], v[128:131], v[202:205], v[108:111]
	v_mfma_f32_16x16x32_bf16 v[104:107], v[146:149], v[202:205], v[104:107]
	v_mfma_f32_16x16x32_bf16 v[100:103], v[128:131], v[232:235], v[100:103]
	v_mfma_f32_16x16x32_bf16 v[96:99], v[146:149], v[232:235], v[96:99]
	v_mfma_f32_16x16x32_bf16 v[124:127], v[132:135], v[190:193], v[124:127]
	v_mfma_f32_16x16x32_bf16 v[120:123], v[150:153], v[190:193], v[120:123]
	v_mfma_f32_16x16x32_bf16 v[116:119], v[132:135], v[198:201], v[116:119]
	v_mfma_f32_16x16x32_bf16 v[112:115], v[150:153], v[198:201], v[112:115]
	v_mfma_f32_16x16x32_bf16 v[108:111], v[132:135], v[228:231], v[108:111]
	v_mfma_f32_16x16x32_bf16 v[104:107], v[150:153], v[228:231], v[104:107]
	v_mfma_f32_16x16x32_bf16 v[100:103], v[132:135], v[236:239], v[100:103]
	v_mfma_f32_16x16x32_bf16 v[96:99], v[150:153], v[236:239], v[96:99]
	s_setprio 0
	s_setprio 1
	v_mfma_f32_16x16x32_bf16 v[64:67], v[170:173], v[186:189], v[64:67]
	v_mfma_f32_16x16x32_bf16 v[60:63], v[178:181], v[186:189], v[60:63]
	v_mfma_f32_16x16x32_bf16 v[52:55], v[170:173], v[194:197], v[52:55]
	v_mfma_f32_16x16x32_bf16 v[48:51], v[178:181], v[194:197], v[48:51]
	v_mfma_f32_16x16x32_bf16 v[44:47], v[170:173], v[202:205], v[44:47]
	v_mfma_f32_16x16x32_bf16 v[40:43], v[178:181], v[202:205], v[40:43]
	v_mfma_f32_16x16x32_bf16 v[36:39], v[170:173], v[232:235], v[36:39]
	v_mfma_f32_16x16x32_bf16 v[32:35], v[178:181], v[232:235], v[32:35]
	v_mfma_f32_16x16x32_bf16 v[64:67], v[174:177], v[190:193], v[64:67]
	v_mfma_f32_16x16x32_bf16 v[60:63], v[182:185], v[190:193], v[60:63]
	v_mfma_f32_16x16x32_bf16 v[52:55], v[174:177], v[198:201], v[52:55]
	v_mfma_f32_16x16x32_bf16 v[48:51], v[182:185], v[198:201], v[48:51]
	v_mfma_f32_16x16x32_bf16 v[44:47], v[174:177], v[228:231], v[44:47]
	v_mfma_f32_16x16x32_bf16 v[40:43], v[182:185], v[228:231], v[40:43]
	v_mfma_f32_16x16x32_bf16 v[36:39], v[174:177], v[236:239], v[36:39]
	v_mfma_f32_16x16x32_bf16 v[32:35], v[182:185], v[236:239], v[32:35]
	s_setprio 0
	s_barrier
	ds_read_b128 v[186:189], v159 offset:49152
	ds_read_b128 v[190:193], v159 offset:50176
	ds_read_b128 v[194:197], v159 offset:51200
	ds_read_b128 v[198:201], v159 offset:52224
	ds_read_b128 v[202:205], v159 offset:53248
	ds_read_b128 v[228:231], v159 offset:54272
	ds_read_b128 v[232:235], v159 offset:55296
	ds_read_b128 v[236:239], v159 offset:56320
	s_add_i32 s22, s45, s77
	s_mov_b32 m0, s22
	v_lshl_add_u64 v[154:155], v[154:155], 0, s[96:97]
	global_load_lds_dwordx4 v[154:155], off
	s_add_i32 m0, s22, 0x2000
	s_add_u32 s20, s20, 0x40080
	v_lshl_add_u64 v[154:155], v[166:167], 0, s[96:97]
	s_addc_u32 s21, s21, 0
	s_add_i32 s22, s46, s77
	global_load_lds_dwordx4 v[154:155], off
	v_lshl_add_u64 v[154:155], s[20:21], 0, v[160:161]
	s_mov_b32 m0, s22
	s_nop 0
	global_load_lds_dwordx4 v[154:155], off
	v_lshl_add_u64 v[154:155], s[20:21], 0, v[136:137]
	s_add_i32 m0, s22, 0x2000
	s_nop 0
	global_load_lds_dwordx4 v[154:155], off
	v_lshl_add_u64 v[154:155], v[168:169], 0, s[96:97]
	s_mov_b32 m0, s35
	s_nop 0
	global_load_lds_dwordx4 v[154:155], off
	v_lshl_add_u64 v[154:155], v[206:207], 0, s[96:97]
	s_mov_b32 m0, s36
	s_nop 0
	global_load_lds_dwordx4 v[154:155], off
	s_waitcnt vmcnt(8)
	s_waitcnt lgkmcnt(0)
	s_barrier
	s_setprio 1
	s_waitcnt lgkmcnt(0)
	v_mfma_f32_16x16x32_bf16 v[92:95], v[128:131], v[186:189], v[92:95]
	v_mfma_f32_16x16x32_bf16 v[88:91], v[146:149], v[186:189], v[88:91]
	v_mfma_f32_16x16x32_bf16 v[84:87], v[128:131], v[194:197], v[84:87]
	v_mfma_f32_16x16x32_bf16 v[80:83], v[146:149], v[194:197], v[80:83]
	v_mfma_f32_16x16x32_bf16 v[76:79], v[128:131], v[202:205], v[76:79]
	v_mfma_f32_16x16x32_bf16 v[72:75], v[146:149], v[202:205], v[72:75]
	v_mfma_f32_16x16x32_bf16 v[68:71], v[128:131], v[232:235], v[68:71]
	v_mfma_f32_16x16x32_bf16 v[56:59], v[146:149], v[232:235], v[56:59]
	v_mfma_f32_16x16x32_bf16 v[92:95], v[132:135], v[190:193], v[92:95]
	v_mfma_f32_16x16x32_bf16 v[88:91], v[150:153], v[190:193], v[88:91]
	v_mfma_f32_16x16x32_bf16 v[84:87], v[132:135], v[198:201], v[84:87]
	v_mfma_f32_16x16x32_bf16 v[80:83], v[150:153], v[198:201], v[80:83]
	v_mfma_f32_16x16x32_bf16 v[76:79], v[132:135], v[228:231], v[76:79]
	v_mfma_f32_16x16x32_bf16 v[72:75], v[150:153], v[228:231], v[72:75]
	v_mfma_f32_16x16x32_bf16 v[68:71], v[132:135], v[236:239], v[68:71]
	v_mfma_f32_16x16x32_bf16 v[56:59], v[150:153], v[236:239], v[56:59]
	s_setprio 0
	s_setprio 1
	v_mfma_f32_16x16x32_bf16 v[28:31], v[170:173], v[186:189], v[28:31]
	v_mfma_f32_16x16x32_bf16 v[24:27], v[178:181], v[186:189], v[24:27]
	v_mfma_f32_16x16x32_bf16 v[20:23], v[170:173], v[194:197], v[20:23]
	v_mfma_f32_16x16x32_bf16 v[16:19], v[178:181], v[194:197], v[16:19]
	v_mfma_f32_16x16x32_bf16 v[12:15], v[170:173], v[202:205], v[12:15]
	v_mfma_f32_16x16x32_bf16 v[8:11], v[178:181], v[202:205], v[8:11]
	v_mfma_f32_16x16x32_bf16 v[4:7], v[170:173], v[232:235], v[4:7]
	v_mfma_f32_16x16x32_bf16 v[0:3], v[178:181], v[232:235], v[0:3]
	v_mfma_f32_16x16x32_bf16 v[28:31], v[174:177], v[190:193], v[28:31]
	v_mfma_f32_16x16x32_bf16 v[24:27], v[182:185], v[190:193], v[24:27]
	v_mfma_f32_16x16x32_bf16 v[20:23], v[174:177], v[198:201], v[20:23]
	v_mfma_f32_16x16x32_bf16 v[16:19], v[182:185], v[198:201], v[16:19]
	v_mfma_f32_16x16x32_bf16 v[12:15], v[174:177], v[228:231], v[12:15]
	v_mfma_f32_16x16x32_bf16 v[8:11], v[182:185], v[228:231], v[8:11]
	v_mfma_f32_16x16x32_bf16 v[4:7], v[174:177], v[236:239], v[4:7]
	v_mfma_f32_16x16x32_bf16 v[0:3], v[182:185], v[236:239], v[0:3]
	s_setprio 0
	s_add_i32 s44, s44, 2
	s_add_u32 s42, s42, 0x100
	s_addc_u32 s43, s43, 0
	s_add_u32 s18, s18, 0x100
	s_addc_u32 s19, s19, 0
	s_cmp_gt_u32 s44, 13
	s_barrier
	s_cbranch_scc0 .LBB0_105
	v_readlane_b32 s18, v253, 23
	v_readlane_b32 s19, v253, 24
	s_and_b64 vcc, exec, s[18:19]
	s_cbranch_vccz .LBB0_108
	s_barrier

.LBB0_127:
	s_add_i32 s47, 0, 0x10000
	v_add_u32_e32 v142, s47, v145
	s_add_i32 s50, 0, 0x14000
	ds_read_b128 v[138:141], v142
	ds_read_b128 v[148:151], v142 offset:1024
	ds_read_b128 v[152:155], v142 offset:2048
	ds_read_b128 v[156:159], v142 offset:3072
	v_add_u32_e32 v142, s50, v145
	ds_read_b128 v[170:173], v142
	ds_read_b128 v[174:177], v142 offset:1024
	ds_read_b128 v[178:181], v142 offset:2048
	ds_read_b128 v[182:185], v142 offset:3072
	v_lshl_add_u64 v[142:143], s[22:23], 0, v[136:137]
	s_add_i32 m0, s31, 0xc000
	ds_read_b128 v[186:189], v147
	ds_read_b128 v[190:193], v147 offset:1024
	ds_read_b128 v[194:197], v147 offset:2048
	ds_read_b128 v[198:201], v147 offset:3072
	ds_read_b128 v[202:205], v147 offset:4096
	ds_read_b128 v[228:231], v147 offset:5120
	ds_read_b128 v[232:235], v147 offset:6144
	ds_read_b128 v[236:239], v147 offset:7168
	s_add_u32 s24, s22, 0xfffe0080
	s_addc_u32 s25, s23, -1
	s_cmp_eq_u32 s46, 4
	s_cselect_b32 s27, s17, s25
	s_cselect_b32 s26, s42, s24
	s_cselect_b32 s25, s15, s45
	s_cselect_b32 s24, s43, s44
	global_load_lds_dwordx4 v[142:143], off
	v_lshl_add_u64 v[142:143], s[22:23], 0, v[134:135]
	s_add_i32 m0, s31, 0xe000
	s_nop 0
	global_load_lds_dwordx4 v[142:143], off
	s_waitcnt vmcnt(8)
	s_waitcnt lgkmcnt(0)
	s_barrier
	s_setprio 1
	s_waitcnt lgkmcnt(0)
	v_mfma_f32_16x16x32_bf16 v[124:127], v[138:141], v[186:189], v[124:127]
	v_mfma_f32_16x16x32_bf16 v[120:123], v[152:155], v[186:189], v[120:123]
	v_mfma_f32_16x16x32_bf16 v[108:111], v[138:141], v[194:197], v[108:111]
	v_mfma_f32_16x16x32_bf16 v[104:107], v[152:155], v[194:197], v[104:107]
	v_mfma_f32_16x16x32_bf16 v[92:95], v[138:141], v[202:205], v[92:95]
	v_mfma_f32_16x16x32_bf16 v[88:91], v[152:155], v[202:205], v[88:91]
	v_mfma_f32_16x16x32_bf16 v[76:79], v[138:141], v[232:235], v[76:79]
	v_mfma_f32_16x16x32_bf16 v[72:75], v[152:155], v[232:235], v[72:75]
	v_mfma_f32_16x16x32_bf16 v[124:127], v[148:151], v[190:193], v[124:127]
	v_mfma_f32_16x16x32_bf16 v[120:123], v[156:159], v[190:193], v[120:123]
	v_mfma_f32_16x16x32_bf16 v[108:111], v[148:151], v[198:201], v[108:111]
	v_mfma_f32_16x16x32_bf16 v[104:107], v[156:159], v[198:201], v[104:107]
	v_mfma_f32_16x16x32_bf16 v[92:95], v[148:151], v[228:231], v[92:95]
	v_mfma_f32_16x16x32_bf16 v[88:91], v[156:159], v[228:231], v[88:91]
	v_mfma_f32_16x16x32_bf16 v[76:79], v[148:151], v[236:239], v[76:79]
	v_mfma_f32_16x16x32_bf16 v[72:75], v[156:159], v[236:239], v[72:75]
	s_setprio 0
	s_setprio 1
	v_mfma_f32_16x16x32_bf16 v[116:119], v[170:173], v[186:189], v[116:119]
	v_mfma_f32_16x16x32_bf16 v[112:115], v[178:181], v[186:189], v[112:115]
	v_mfma_f32_16x16x32_bf16 v[100:103], v[170:173], v[194:197], v[100:103]
	v_mfma_f32_16x16x32_bf16 v[96:99], v[178:181], v[194:197], v[96:99]
	v_mfma_f32_16x16x32_bf16 v[84:87], v[170:173], v[202:205], v[84:87]
	v_mfma_f32_16x16x32_bf16 v[80:83], v[178:181], v[202:205], v[80:83]
	v_mfma_f32_16x16x32_bf16 v[68:71], v[170:173], v[232:235], v[68:71]
	v_mfma_f32_16x16x32_bf16 v[64:67], v[178:181], v[232:235], v[64:67]
	v_mfma_f32_16x16x32_bf16 v[116:119], v[174:177], v[190:193], v[116:119]
	v_mfma_f32_16x16x32_bf16 v[112:115], v[182:185], v[190:193], v[112:115]
	v_mfma_f32_16x16x32_bf16 v[100:103], v[174:177], v[198:201], v[100:103]
	v_mfma_f32_16x16x32_bf16 v[96:99], v[182:185], v[198:201], v[96:99]
	v_mfma_f32_16x16x32_bf16 v[84:87], v[174:177], v[228:231], v[84:87]
	v_mfma_f32_16x16x32_bf16 v[80:83], v[182:185], v[228:231], v[80:83]
	v_mfma_f32_16x16x32_bf16 v[68:71], v[174:177], v[236:239], v[68:71]
	v_mfma_f32_16x16x32_bf16 v[64:67], v[182:185], v[236:239], v[64:67]
	s_setprio 0
	s_barrier
	ds_read_b128 v[186:189], v147 offset:16384
	ds_read_b128 v[190:193], v147 offset:17408
	ds_read_b128 v[194:197], v147 offset:18432
	ds_read_b128 v[198:201], v147 offset:19456
	ds_read_b128 v[202:205], v147 offset:20480
	ds_read_b128 v[228:231], v147 offset:21504
	ds_read_b128 v[232:235], v147 offset:22528
	ds_read_b128 v[236:239], v147 offset:23552
	s_add_i32 s47, s47, s77
	s_mov_b32 m0, s47
	v_lshl_add_u64 v[142:143], s[24:25], 0, v[160:161]
	global_load_lds_dwordx4 v[142:143], off
	s_add_i32 m0, s47, 0x2000
	s_add_u32 s48, s24, 0x20000
	v_lshl_add_u64 v[166:167], s[24:25], 0, v[128:129]
	s_addc_u32 s49, s25, 0
	s_add_i32 s47, s50, s77
	global_load_lds_dwordx4 v[166:167], off
	v_lshl_add_u64 v[168:169], s[48:49], 0, v[160:161]
	s_mov_b32 m0, s47
	v_lshl_add_u64 v[206:207], s[26:27], 0, v[130:131]
	global_load_lds_dwordx4 v[168:169], off
	v_lshl_add_u64 v[168:169], s[48:49], 0, v[128:129]
	s_add_i32 m0, s47, 0x2000
	s_nop 0
	global_load_lds_dwordx4 v[168:169], off
	v_lshl_add_u64 v[168:169], s[26:27], 0, v[132:133]
	s_mov_b32 m0, s31
	s_nop 0
	global_load_lds_dwordx4 v[168:169], off
	s_mov_b32 m0, s34
	s_nop 0
	global_load_lds_dwordx4 v[206:207], off
	s_waitcnt vmcnt(8)
	s_waitcnt lgkmcnt(0)
	s_barrier
	s_setprio 1
	s_waitcnt lgkmcnt(0)
	v_mfma_f32_16x16x32_bf16 v[60:63], v[138:141], v[186:189], v[60:63]
	v_mfma_f32_16x16x32_bf16 v[56:59], v[152:155], v[186:189], v[56:59]
	v_mfma_f32_16x16x32_bf16 v[44:47], v[138:141], v[194:197], v[44:47]
	v_mfma_f32_16x16x32_bf16 v[40:43], v[152:155], v[194:197], v[40:43]
	v_mfma_f32_16x16x32_bf16 v[28:31], v[138:141], v[202:205], v[28:31]
	v_mfma_f32_16x16x32_bf16 v[24:27], v[152:155], v[202:205], v[24:27]
	v_mfma_f32_16x16x32_bf16 v[12:15], v[138:141], v[232:235], v[12:15]
	v_mfma_f32_16x16x32_bf16 v[8:11], v[152:155], v[232:235], v[8:11]
	v_mfma_f32_16x16x32_bf16 v[60:63], v[148:151], v[190:193], v[60:63]
	v_mfma_f32_16x16x32_bf16 v[56:59], v[156:159], v[190:193], v[56:59]
	v_mfma_f32_16x16x32_bf16 v[44:47], v[148:151], v[198:201], v[44:47]
	v_mfma_f32_16x16x32_bf16 v[40:43], v[156:159], v[198:201], v[40:43]
	v_mfma_f32_16x16x32_bf16 v[28:31], v[148:151], v[228:231], v[28:31]
	v_mfma_f32_16x16x32_bf16 v[24:27], v[156:159], v[228:231], v[24:27]
	v_mfma_f32_16x16x32_bf16 v[12:15], v[148:151], v[236:239], v[12:15]
	v_mfma_f32_16x16x32_bf16 v[8:11], v[156:159], v[236:239], v[8:11]
	s_setprio 0
	s_setprio 1
	v_mfma_f32_16x16x32_bf16 v[52:55], v[170:173], v[186:189], v[52:55]
	v_mfma_f32_16x16x32_bf16 v[48:51], v[178:181], v[186:189], v[48:51]
	v_mfma_f32_16x16x32_bf16 v[36:39], v[170:173], v[194:197], v[36:39]
	v_mfma_f32_16x16x32_bf16 v[32:35], v[178:181], v[194:197], v[32:35]
	v_mfma_f32_16x16x32_bf16 v[20:23], v[170:173], v[202:205], v[20:23]
	v_mfma_f32_16x16x32_bf16 v[16:19], v[178:181], v[202:205], v[16:19]
	v_mfma_f32_16x16x32_bf16 v[4:7], v[170:173], v[232:235], v[4:7]
	v_mfma_f32_16x16x32_bf16 v[0:3], v[178:181], v[232:235], v[0:3]
	v_mfma_f32_16x16x32_bf16 v[52:55], v[174:177], v[190:193], v[52:55]
	v_mfma_f32_16x16x32_bf16 v[48:51], v[182:185], v[190:193], v[48:51]
	v_mfma_f32_16x16x32_bf16 v[36:39], v[174:177], v[198:201], v[36:39]
	v_mfma_f32_16x16x32_bf16 v[32:35], v[182:185], v[198:201], v[32:35]
	v_mfma_f32_16x16x32_bf16 v[20:23], v[174:177], v[228:231], v[20:23]
	v_mfma_f32_16x16x32_bf16 v[16:19], v[182:185], v[228:231], v[16:19]
	v_mfma_f32_16x16x32_bf16 v[4:7], v[174:177], v[236:239], v[4:7]
	v_mfma_f32_16x16x32_bf16 v[0:3], v[182:185], v[236:239], v[0:3]
	s_setprio 0
	s_barrier
	s_add_i32 s47, 0, 0x18000
	s_add_i32 s48, 0, 0x1c000
	v_add_u32_e32 v156, s47, v145
	v_add_u32_e32 v182, s48, v145
	ds_read_b128 v[138:141], v156
	ds_read_b128 v[148:151], v156 offset:1024
	ds_read_b128 v[152:155], v156 offset:2048
	ds_read_b128 v[156:159], v156 offset:3072
	ds_read_b128 v[170:173], v182
	ds_read_b128 v[174:177], v182 offset:1024
	ds_read_b128 v[178:181], v182 offset:2048
	ds_read_b128 v[182:185], v182 offset:3072
	s_add_u32 s26, s26, 0x20000
	s_addc_u32 s27, s27, 0
	s_mov_b32 m0, s35
	v_lshl_add_u64 v[240:241], s[26:27], 0, v[132:133]
	ds_read_b128 v[186:189], v147 offset:32768
	ds_read_b128 v[190:193], v147 offset:33792
	ds_read_b128 v[194:197], v147 offset:34816
	ds_read_b128 v[198:201], v147 offset:35840
	ds_read_b128 v[202:205], v147 offset:36864
	ds_read_b128 v[228:231], v147 offset:37888
	ds_read_b128 v[232:235], v147 offset:38912
	ds_read_b128 v[236:239], v147 offset:39936
	global_load_lds_dwordx4 v[240:241], off
	v_lshl_add_u64 v[240:241], s[26:27], 0, v[130:131]
	s_mov_b32 m0, s36
	s_nop 0
	global_load_lds_dwordx4 v[240:241], off
	s_waitcnt vmcnt(8)
	s_waitcnt lgkmcnt(0)
	s_barrier
	s_setprio 1
	s_waitcnt lgkmcnt(0)
	v_mfma_f32_16x16x32_bf16 v[124:127], v[138:141], v[186:189], v[124:127]
	v_mfma_f32_16x16x32_bf16 v[120:123], v[152:155], v[186:189], v[120:123]
	v_mfma_f32_16x16x32_bf16 v[108:111], v[138:141], v[194:197], v[108:111]
	v_mfma_f32_16x16x32_bf16 v[104:107], v[152:155], v[194:197], v[104:107]
	v_mfma_f32_16x16x32_bf16 v[92:95], v[138:141], v[202:205], v[92:95]
	v_mfma_f32_16x16x32_bf16 v[88:91], v[152:155], v[202:205], v[88:91]
	v_mfma_f32_16x16x32_bf16 v[76:79], v[138:141], v[232:235], v[76:79]
	v_mfma_f32_16x16x32_bf16 v[72:75], v[152:155], v[232:235], v[72:75]
	v_mfma_f32_16x16x32_bf16 v[124:127], v[148:151], v[190:193], v[124:127]
	v_mfma_f32_16x16x32_bf16 v[120:123], v[156:159], v[190:193], v[120:123]
	v_mfma_f32_16x16x32_bf16 v[108:111], v[148:151], v[198:201], v[108:111]
	v_mfma_f32_16x16x32_bf16 v[104:107], v[156:159], v[198:201], v[104:107]
	v_mfma_f32_16x16x32_bf16 v[92:95], v[148:151], v[228:231], v[92:95]
	v_mfma_f32_16x16x32_bf16 v[88:91], v[156:159], v[228:231], v[88:91]
	v_mfma_f32_16x16x32_bf16 v[76:79], v[148:151], v[236:239], v[76:79]
	v_mfma_f32_16x16x32_bf16 v[72:75], v[156:159], v[236:239], v[72:75]
	s_setprio 0
	s_setprio 1
	v_mfma_f32_16x16x32_bf16 v[116:119], v[170:173], v[186:189], v[116:119]
	v_mfma_f32_16x16x32_bf16 v[112:115], v[178:181], v[186:189], v[112:115]
	v_mfma_f32_16x16x32_bf16 v[100:103], v[170:173], v[194:197], v[100:103]
	v_mfma_f32_16x16x32_bf16 v[96:99], v[178:181], v[194:197], v[96:99]
	v_mfma_f32_16x16x32_bf16 v[84:87], v[170:173], v[202:205], v[84:87]
	v_mfma_f32_16x16x32_bf16 v[80:83], v[178:181], v[202:205], v[80:83]
	v_mfma_f32_16x16x32_bf16 v[68:71], v[170:173], v[232:235], v[68:71]
	v_mfma_f32_16x16x32_bf16 v[64:67], v[178:181], v[232:235], v[64:67]
	v_mfma_f32_16x16x32_bf16 v[116:119], v[174:177], v[190:193], v[116:119]
	v_mfma_f32_16x16x32_bf16 v[112:115], v[182:185], v[190:193], v[112:115]
	v_mfma_f32_16x16x32_bf16 v[100:103], v[174:177], v[198:201], v[100:103]
	v_mfma_f32_16x16x32_bf16 v[96:99], v[182:185], v[198:201], v[96:99]
	v_mfma_f32_16x16x32_bf16 v[84:87], v[174:177], v[228:231], v[84:87]
	v_mfma_f32_16x16x32_bf16 v[80:83], v[182:185], v[228:231], v[80:83]
	v_mfma_f32_16x16x32_bf16 v[68:71], v[174:177], v[236:239], v[68:71]
	v_mfma_f32_16x16x32_bf16 v[64:67], v[182:185], v[236:239], v[64:67]
	s_setprio 0
	s_barrier
	ds_read_b128 v[186:189], v147 offset:49152
	ds_read_b128 v[190:193], v147 offset:50176
	ds_read_b128 v[194:197], v147 offset:51200
	ds_read_b128 v[198:201], v147 offset:52224
	ds_read_b128 v[202:205], v147 offset:53248
	ds_read_b128 v[228:231], v147 offset:54272
	ds_read_b128 v[232:235], v147 offset:55296
	ds_read_b128 v[236:239], v147 offset:56320
	s_add_i32 s26, s47, s77
	s_mov_b32 m0, s26
	v_lshl_add_u64 v[142:143], v[142:143], 0, s[96:97]
	global_load_lds_dwordx4 v[142:143], off
	s_add_i32 m0, s26, 0x2000
	s_add_u32 s24, s24, 0x20080
	v_lshl_add_u64 v[142:143], v[166:167], 0, s[96:97]
	s_addc_u32 s25, s25, 0
	s_add_i32 s26, s48, s77
	global_load_lds_dwordx4 v[142:143], off
	v_lshl_add_u64 v[142:143], s[24:25], 0, v[160:161]
	s_mov_b32 m0, s26
	s_nop 0
	global_load_lds_dwordx4 v[142:143], off
	v_lshl_add_u64 v[142:143], s[24:25], 0, v[128:129]
	s_add_i32 m0, s26, 0x2000
	s_nop 0
	global_load_lds_dwordx4 v[142:143], off
	v_lshl_add_u64 v[142:143], v[168:169], 0, s[96:97]
	s_mov_b32 m0, s37
	s_nop 0
	global_load_lds_dwordx4 v[142:143], off
	v_lshl_add_u64 v[142:143], v[206:207], 0, s[96:97]
	s_mov_b32 m0, s38
	s_nop 0
	global_load_lds_dwordx4 v[142:143], off
	s_waitcnt vmcnt(8)
	s_waitcnt lgkmcnt(0)
	s_barrier
	s_setprio 1
	s_waitcnt lgkmcnt(0)
	v_mfma_f32_16x16x32_bf16 v[60:63], v[138:141], v[186:189], v[60:63]
	v_mfma_f32_16x16x32_bf16 v[56:59], v[152:155], v[186:189], v[56:59]
	v_mfma_f32_16x16x32_bf16 v[44:47], v[138:141], v[194:197], v[44:47]
	v_mfma_f32_16x16x32_bf16 v[40:43], v[152:155], v[194:197], v[40:43]
	v_mfma_f32_16x16x32_bf16 v[28:31], v[138:141], v[202:205], v[28:31]
	v_mfma_f32_16x16x32_bf16 v[24:27], v[152:155], v[202:205], v[24:27]
	v_mfma_f32_16x16x32_bf16 v[12:15], v[138:141], v[232:235], v[12:15]
	v_mfma_f32_16x16x32_bf16 v[8:11], v[152:155], v[232:235], v[8:11]
	v_mfma_f32_16x16x32_bf16 v[60:63], v[148:151], v[190:193], v[60:63]
	v_mfma_f32_16x16x32_bf16 v[56:59], v[156:159], v[190:193], v[56:59]
	v_mfma_f32_16x16x32_bf16 v[44:47], v[148:151], v[198:201], v[44:47]
	v_mfma_f32_16x16x32_bf16 v[40:43], v[156:159], v[198:201], v[40:43]
	v_mfma_f32_16x16x32_bf16 v[28:31], v[148:151], v[228:231], v[28:31]
	v_mfma_f32_16x16x32_bf16 v[24:27], v[156:159], v[228:231], v[24:27]
	v_mfma_f32_16x16x32_bf16 v[12:15], v[148:151], v[236:239], v[12:15]
	v_mfma_f32_16x16x32_bf16 v[8:11], v[156:159], v[236:239], v[8:11]
	s_setprio 0
	s_setprio 1
	v_mfma_f32_16x16x32_bf16 v[52:55], v[170:173], v[186:189], v[52:55]
	v_mfma_f32_16x16x32_bf16 v[48:51], v[178:181], v[186:189], v[48:51]
	v_mfma_f32_16x16x32_bf16 v[36:39], v[170:173], v[194:197], v[36:39]
	v_mfma_f32_16x16x32_bf16 v[32:35], v[178:181], v[194:197], v[32:35]
	v_mfma_f32_16x16x32_bf16 v[20:23], v[170:173], v[202:205], v[20:23]
	v_mfma_f32_16x16x32_bf16 v[16:19], v[178:181], v[202:205], v[16:19]
	v_mfma_f32_16x16x32_bf16 v[4:7], v[170:173], v[232:235], v[4:7]
	v_mfma_f32_16x16x32_bf16 v[0:3], v[178:181], v[232:235], v[0:3]
	v_mfma_f32_16x16x32_bf16 v[52:55], v[174:177], v[190:193], v[52:55]
	v_mfma_f32_16x16x32_bf16 v[48:51], v[182:185], v[190:193], v[48:51]
	v_mfma_f32_16x16x32_bf16 v[36:39], v[174:177], v[198:201], v[36:39]
	v_mfma_f32_16x16x32_bf16 v[32:35], v[182:185], v[198:201], v[32:35]
	v_mfma_f32_16x16x32_bf16 v[20:23], v[174:177], v[228:231], v[20:23]
	v_mfma_f32_16x16x32_bf16 v[16:19], v[182:185], v[228:231], v[16:19]
	v_mfma_f32_16x16x32_bf16 v[4:7], v[174:177], v[236:239], v[4:7]
	v_mfma_f32_16x16x32_bf16 v[0:3], v[182:185], v[236:239], v[0:3]
	s_setprio 0
	s_add_i32 s46, s46, 2
	s_add_u32 s44, s44, 0x100
	s_addc_u32 s45, s45, 0
	s_add_u32 s22, s22, 0x100
	s_addc_u32 s23, s23, 0
	s_cmp_gt_u32 s46, 5
	s_barrier
	s_cbranch_scc0 .LBB0_127
	v_readlane_b32 s22, v253, 23
	v_readlane_b32 s23, v253, 24
	s_and_b64 vcc, exec, s[22:23]
	s_cbranch_vccz .LBB0_130
	s_barrier

.LBB0_147:
	s_add_i32 s47, 0, 0x10000
	v_add_u32_e32 v142, s47, v145
	s_add_i32 s50, 0, 0x14000
	ds_read_b128 v[138:141], v142
	ds_read_b128 v[148:151], v142 offset:1024
	ds_read_b128 v[152:155], v142 offset:2048
	ds_read_b128 v[156:159], v142 offset:3072
	v_add_u32_e32 v142, s50, v145
	ds_read_b128 v[170:173], v142
	ds_read_b128 v[174:177], v142 offset:1024
	ds_read_b128 v[178:181], v142 offset:2048
	ds_read_b128 v[182:185], v142 offset:3072
	v_lshl_add_u64 v[142:143], s[22:23], 0, v[136:137]
	s_add_i32 m0, s34, 0xc000
	ds_read_b128 v[186:189], v147
	ds_read_b128 v[190:193], v147 offset:1024
	ds_read_b128 v[194:197], v147 offset:2048
	ds_read_b128 v[198:201], v147 offset:3072
	ds_read_b128 v[202:205], v147 offset:4096
	ds_read_b128 v[228:231], v147 offset:5120
	ds_read_b128 v[232:235], v147 offset:6144
	ds_read_b128 v[236:239], v147 offset:7168
	s_add_u32 s24, s22, 0xfffe0080
	s_addc_u32 s25, s23, -1
	s_cmp_eq_u32 s46, 4
	s_cselect_b32 s27, s17, s25
	s_cselect_b32 s26, s42, s24
	s_cselect_b32 s25, s15, s45
	s_cselect_b32 s24, s43, s44
	global_load_lds_dwordx4 v[142:143], off
	v_lshl_add_u64 v[142:143], s[22:23], 0, v[134:135]
	s_add_i32 m0, s34, 0xe000
	s_nop 0
	global_load_lds_dwordx4 v[142:143], off
	s_waitcnt vmcnt(8)
	s_waitcnt lgkmcnt(0)
	s_barrier
	s_setprio 1
	s_waitcnt lgkmcnt(0)
	v_mfma_f32_16x16x32_bf16 v[124:127], v[138:141], v[186:189], v[124:127]
	v_mfma_f32_16x16x32_bf16 v[120:123], v[152:155], v[186:189], v[120:123]
	v_mfma_f32_16x16x32_bf16 v[108:111], v[138:141], v[194:197], v[108:111]
	v_mfma_f32_16x16x32_bf16 v[104:107], v[152:155], v[194:197], v[104:107]
	v_mfma_f32_16x16x32_bf16 v[92:95], v[138:141], v[202:205], v[92:95]
	v_mfma_f32_16x16x32_bf16 v[88:91], v[152:155], v[202:205], v[88:91]
	v_mfma_f32_16x16x32_bf16 v[76:79], v[138:141], v[232:235], v[76:79]
	v_mfma_f32_16x16x32_bf16 v[72:75], v[152:155], v[232:235], v[72:75]
	v_mfma_f32_16x16x32_bf16 v[124:127], v[148:151], v[190:193], v[124:127]
	v_mfma_f32_16x16x32_bf16 v[120:123], v[156:159], v[190:193], v[120:123]
	v_mfma_f32_16x16x32_bf16 v[108:111], v[148:151], v[198:201], v[108:111]
	v_mfma_f32_16x16x32_bf16 v[104:107], v[156:159], v[198:201], v[104:107]
	v_mfma_f32_16x16x32_bf16 v[92:95], v[148:151], v[228:231], v[92:95]
	v_mfma_f32_16x16x32_bf16 v[88:91], v[156:159], v[228:231], v[88:91]
	v_mfma_f32_16x16x32_bf16 v[76:79], v[148:151], v[236:239], v[76:79]
	v_mfma_f32_16x16x32_bf16 v[72:75], v[156:159], v[236:239], v[72:75]
	s_setprio 0
	s_setprio 1
	v_mfma_f32_16x16x32_bf16 v[116:119], v[170:173], v[186:189], v[116:119]
	v_mfma_f32_16x16x32_bf16 v[112:115], v[178:181], v[186:189], v[112:115]
	v_mfma_f32_16x16x32_bf16 v[100:103], v[170:173], v[194:197], v[100:103]
	v_mfma_f32_16x16x32_bf16 v[96:99], v[178:181], v[194:197], v[96:99]
	v_mfma_f32_16x16x32_bf16 v[84:87], v[170:173], v[202:205], v[84:87]
	v_mfma_f32_16x16x32_bf16 v[80:83], v[178:181], v[202:205], v[80:83]
	v_mfma_f32_16x16x32_bf16 v[68:71], v[170:173], v[232:235], v[68:71]
	v_mfma_f32_16x16x32_bf16 v[64:67], v[178:181], v[232:235], v[64:67]
	v_mfma_f32_16x16x32_bf16 v[116:119], v[174:177], v[190:193], v[116:119]
	v_mfma_f32_16x16x32_bf16 v[112:115], v[182:185], v[190:193], v[112:115]
	v_mfma_f32_16x16x32_bf16 v[100:103], v[174:177], v[198:201], v[100:103]
	v_mfma_f32_16x16x32_bf16 v[96:99], v[182:185], v[198:201], v[96:99]
	v_mfma_f32_16x16x32_bf16 v[84:87], v[174:177], v[228:231], v[84:87]
	v_mfma_f32_16x16x32_bf16 v[80:83], v[182:185], v[228:231], v[80:83]
	v_mfma_f32_16x16x32_bf16 v[68:71], v[174:177], v[236:239], v[68:71]
	v_mfma_f32_16x16x32_bf16 v[64:67], v[182:185], v[236:239], v[64:67]
	s_setprio 0
	s_barrier
	ds_read_b128 v[186:189], v147 offset:16384
	ds_read_b128 v[190:193], v147 offset:17408
	ds_read_b128 v[194:197], v147 offset:18432
	ds_read_b128 v[198:201], v147 offset:19456
	ds_read_b128 v[202:205], v147 offset:20480
	ds_read_b128 v[228:231], v147 offset:21504
	ds_read_b128 v[232:235], v147 offset:22528
	ds_read_b128 v[236:239], v147 offset:23552
	s_add_i32 s47, s47, s77
	s_mov_b32 m0, s47
	v_lshl_add_u64 v[142:143], s[24:25], 0, v[160:161]
	global_load_lds_dwordx4 v[142:143], off
	s_add_i32 m0, s47, 0x2000
	s_add_u32 s48, s24, 0x20000
	v_lshl_add_u64 v[166:167], s[24:25], 0, v[128:129]
	s_addc_u32 s49, s25, 0
	s_add_i32 s47, s50, s77
	global_load_lds_dwordx4 v[166:167], off
	v_lshl_add_u64 v[168:169], s[48:49], 0, v[160:161]
	s_mov_b32 m0, s47
	v_lshl_add_u64 v[206:207], s[26:27], 0, v[130:131]
	global_load_lds_dwordx4 v[168:169], off
	v_lshl_add_u64 v[168:169], s[48:49], 0, v[128:129]
	s_add_i32 m0, s47, 0x2000
	s_nop 0
	global_load_lds_dwordx4 v[168:169], off
	v_lshl_add_u64 v[168:169], s[26:27], 0, v[132:133]
	s_mov_b32 m0, s34
	s_nop 0
	global_load_lds_dwordx4 v[168:169], off
	s_mov_b32 m0, s35
	s_nop 0
	global_load_lds_dwordx4 v[206:207], off
	s_waitcnt vmcnt(8)
	s_waitcnt lgkmcnt(0)
	s_barrier
	s_setprio 1
	s_waitcnt lgkmcnt(0)
	v_mfma_f32_16x16x32_bf16 v[60:63], v[138:141], v[186:189], v[60:63]
	v_mfma_f32_16x16x32_bf16 v[56:59], v[152:155], v[186:189], v[56:59]
	v_mfma_f32_16x16x32_bf16 v[44:47], v[138:141], v[194:197], v[44:47]
	v_mfma_f32_16x16x32_bf16 v[40:43], v[152:155], v[194:197], v[40:43]
	v_mfma_f32_16x16x32_bf16 v[28:31], v[138:141], v[202:205], v[28:31]
	v_mfma_f32_16x16x32_bf16 v[24:27], v[152:155], v[202:205], v[24:27]
	v_mfma_f32_16x16x32_bf16 v[12:15], v[138:141], v[232:235], v[12:15]
	v_mfma_f32_16x16x32_bf16 v[8:11], v[152:155], v[232:235], v[8:11]
	v_mfma_f32_16x16x32_bf16 v[60:63], v[148:151], v[190:193], v[60:63]
	v_mfma_f32_16x16x32_bf16 v[56:59], v[156:159], v[190:193], v[56:59]
	v_mfma_f32_16x16x32_bf16 v[44:47], v[148:151], v[198:201], v[44:47]
	v_mfma_f32_16x16x32_bf16 v[40:43], v[156:159], v[198:201], v[40:43]
	v_mfma_f32_16x16x32_bf16 v[28:31], v[148:151], v[228:231], v[28:31]
	v_mfma_f32_16x16x32_bf16 v[24:27], v[156:159], v[228:231], v[24:27]
	v_mfma_f32_16x16x32_bf16 v[12:15], v[148:151], v[236:239], v[12:15]
	v_mfma_f32_16x16x32_bf16 v[8:11], v[156:159], v[236:239], v[8:11]
	s_setprio 0
	s_setprio 1
	v_mfma_f32_16x16x32_bf16 v[52:55], v[170:173], v[186:189], v[52:55]
	v_mfma_f32_16x16x32_bf16 v[48:51], v[178:181], v[186:189], v[48:51]
	v_mfma_f32_16x16x32_bf16 v[36:39], v[170:173], v[194:197], v[36:39]
	v_mfma_f32_16x16x32_bf16 v[32:35], v[178:181], v[194:197], v[32:35]
	v_mfma_f32_16x16x32_bf16 v[20:23], v[170:173], v[202:205], v[20:23]
	v_mfma_f32_16x16x32_bf16 v[16:19], v[178:181], v[202:205], v[16:19]
	v_mfma_f32_16x16x32_bf16 v[4:7], v[170:173], v[232:235], v[4:7]
	v_mfma_f32_16x16x32_bf16 v[0:3], v[178:181], v[232:235], v[0:3]
	v_mfma_f32_16x16x32_bf16 v[52:55], v[174:177], v[190:193], v[52:55]
	v_mfma_f32_16x16x32_bf16 v[48:51], v[182:185], v[190:193], v[48:51]
	v_mfma_f32_16x16x32_bf16 v[36:39], v[174:177], v[198:201], v[36:39]
	v_mfma_f32_16x16x32_bf16 v[32:35], v[182:185], v[198:201], v[32:35]
	v_mfma_f32_16x16x32_bf16 v[20:23], v[174:177], v[228:231], v[20:23]
	v_mfma_f32_16x16x32_bf16 v[16:19], v[182:185], v[228:231], v[16:19]
	v_mfma_f32_16x16x32_bf16 v[4:7], v[174:177], v[236:239], v[4:7]
	v_mfma_f32_16x16x32_bf16 v[0:3], v[182:185], v[236:239], v[0:3]
	s_setprio 0
	s_barrier
	s_add_i32 s47, 0, 0x18000
	s_add_i32 s48, 0, 0x1c000
	v_add_u32_e32 v156, s47, v145
	v_add_u32_e32 v182, s48, v145
	ds_read_b128 v[138:141], v156
	ds_read_b128 v[148:151], v156 offset:1024
	ds_read_b128 v[152:155], v156 offset:2048
	ds_read_b128 v[156:159], v156 offset:3072
	ds_read_b128 v[170:173], v182
	ds_read_b128 v[174:177], v182 offset:1024
	ds_read_b128 v[178:181], v182 offset:2048
	ds_read_b128 v[182:185], v182 offset:3072
	s_add_u32 s26, s26, 0x20000
	s_addc_u32 s27, s27, 0
	s_mov_b32 m0, s36
	v_lshl_add_u64 v[240:241], s[26:27], 0, v[132:133]
	ds_read_b128 v[186:189], v147 offset:32768
	ds_read_b128 v[190:193], v147 offset:33792
	ds_read_b128 v[194:197], v147 offset:34816
	ds_read_b128 v[198:201], v147 offset:35840
	ds_read_b128 v[202:205], v147 offset:36864
	ds_read_b128 v[228:231], v147 offset:37888
	ds_read_b128 v[232:235], v147 offset:38912
	ds_read_b128 v[236:239], v147 offset:39936
	global_load_lds_dwordx4 v[240:241], off
	v_lshl_add_u64 v[240:241], s[26:27], 0, v[130:131]
	s_mov_b32 m0, s37
	s_nop 0
	global_load_lds_dwordx4 v[240:241], off
	s_waitcnt vmcnt(8)
	s_waitcnt lgkmcnt(0)
	s_barrier
	s_setprio 1
	s_waitcnt lgkmcnt(0)
	v_mfma_f32_16x16x32_bf16 v[124:127], v[138:141], v[186:189], v[124:127]
	v_mfma_f32_16x16x32_bf16 v[120:123], v[152:155], v[186:189], v[120:123]
	v_mfma_f32_16x16x32_bf16 v[108:111], v[138:141], v[194:197], v[108:111]
	v_mfma_f32_16x16x32_bf16 v[104:107], v[152:155], v[194:197], v[104:107]
	v_mfma_f32_16x16x32_bf16 v[92:95], v[138:141], v[202:205], v[92:95]
	v_mfma_f32_16x16x32_bf16 v[88:91], v[152:155], v[202:205], v[88:91]
	v_mfma_f32_16x16x32_bf16 v[76:79], v[138:141], v[232:235], v[76:79]
	v_mfma_f32_16x16x32_bf16 v[72:75], v[152:155], v[232:235], v[72:75]
	v_mfma_f32_16x16x32_bf16 v[124:127], v[148:151], v[190:193], v[124:127]
	v_mfma_f32_16x16x32_bf16 v[120:123], v[156:159], v[190:193], v[120:123]
	v_mfma_f32_16x16x32_bf16 v[108:111], v[148:151], v[198:201], v[108:111]
	v_mfma_f32_16x16x32_bf16 v[104:107], v[156:159], v[198:201], v[104:107]
	v_mfma_f32_16x16x32_bf16 v[92:95], v[148:151], v[228:231], v[92:95]
	v_mfma_f32_16x16x32_bf16 v[88:91], v[156:159], v[228:231], v[88:91]
	v_mfma_f32_16x16x32_bf16 v[76:79], v[148:151], v[236:239], v[76:79]
	v_mfma_f32_16x16x32_bf16 v[72:75], v[156:159], v[236:239], v[72:75]
	s_setprio 0
	s_setprio 1
	v_mfma_f32_16x16x32_bf16 v[116:119], v[170:173], v[186:189], v[116:119]
	v_mfma_f32_16x16x32_bf16 v[112:115], v[178:181], v[186:189], v[112:115]
	v_mfma_f32_16x16x32_bf16 v[100:103], v[170:173], v[194:197], v[100:103]
	v_mfma_f32_16x16x32_bf16 v[96:99], v[178:181], v[194:197], v[96:99]
	v_mfma_f32_16x16x32_bf16 v[84:87], v[170:173], v[202:205], v[84:87]
	v_mfma_f32_16x16x32_bf16 v[80:83], v[178:181], v[202:205], v[80:83]
	v_mfma_f32_16x16x32_bf16 v[68:71], v[170:173], v[232:235], v[68:71]
	v_mfma_f32_16x16x32_bf16 v[64:67], v[178:181], v[232:235], v[64:67]
	v_mfma_f32_16x16x32_bf16 v[116:119], v[174:177], v[190:193], v[116:119]
	v_mfma_f32_16x16x32_bf16 v[112:115], v[182:185], v[190:193], v[112:115]
	v_mfma_f32_16x16x32_bf16 v[100:103], v[174:177], v[198:201], v[100:103]
	v_mfma_f32_16x16x32_bf16 v[96:99], v[182:185], v[198:201], v[96:99]
	v_mfma_f32_16x16x32_bf16 v[84:87], v[174:177], v[228:231], v[84:87]
	v_mfma_f32_16x16x32_bf16 v[80:83], v[182:185], v[228:231], v[80:83]
	v_mfma_f32_16x16x32_bf16 v[68:71], v[174:177], v[236:239], v[68:71]
	v_mfma_f32_16x16x32_bf16 v[64:67], v[182:185], v[236:239], v[64:67]
	s_setprio 0
	s_barrier
	ds_read_b128 v[186:189], v147 offset:49152
	ds_read_b128 v[190:193], v147 offset:50176
	ds_read_b128 v[194:197], v147 offset:51200
	ds_read_b128 v[198:201], v147 offset:52224
	ds_read_b128 v[202:205], v147 offset:53248
	ds_read_b128 v[228:231], v147 offset:54272
	ds_read_b128 v[232:235], v147 offset:55296
	ds_read_b128 v[236:239], v147 offset:56320
	s_add_i32 s26, s47, s77
	s_mov_b32 m0, s26
	v_lshl_add_u64 v[142:143], v[142:143], 0, s[96:97]
	global_load_lds_dwordx4 v[142:143], off
	s_add_i32 m0, s26, 0x2000
	s_add_u32 s24, s24, 0x20080
	v_lshl_add_u64 v[142:143], v[166:167], 0, s[96:97]
	s_addc_u32 s25, s25, 0
	s_add_i32 s26, s48, s77
	global_load_lds_dwordx4 v[142:143], off
	v_lshl_add_u64 v[142:143], s[24:25], 0, v[160:161]
	s_mov_b32 m0, s26
	s_nop 0
	global_load_lds_dwordx4 v[142:143], off
	v_lshl_add_u64 v[142:143], s[24:25], 0, v[128:129]
	s_add_i32 m0, s26, 0x2000
	s_nop 0
	global_load_lds_dwordx4 v[142:143], off
	v_lshl_add_u64 v[142:143], v[168:169], 0, s[96:97]
	s_mov_b32 m0, s38
	s_nop 0
	global_load_lds_dwordx4 v[142:143], off
	v_lshl_add_u64 v[142:143], v[206:207], 0, s[96:97]
	s_mov_b32 m0, s39
	s_nop 0
	global_load_lds_dwordx4 v[142:143], off
	s_waitcnt vmcnt(8)
	s_waitcnt lgkmcnt(0)
	s_barrier
	s_setprio 1
	s_waitcnt lgkmcnt(0)
	v_mfma_f32_16x16x32_bf16 v[60:63], v[138:141], v[186:189], v[60:63]
	v_mfma_f32_16x16x32_bf16 v[56:59], v[152:155], v[186:189], v[56:59]
	v_mfma_f32_16x16x32_bf16 v[44:47], v[138:141], v[194:197], v[44:47]
	v_mfma_f32_16x16x32_bf16 v[40:43], v[152:155], v[194:197], v[40:43]
	v_mfma_f32_16x16x32_bf16 v[28:31], v[138:141], v[202:205], v[28:31]
	v_mfma_f32_16x16x32_bf16 v[24:27], v[152:155], v[202:205], v[24:27]
	v_mfma_f32_16x16x32_bf16 v[12:15], v[138:141], v[232:235], v[12:15]
	v_mfma_f32_16x16x32_bf16 v[8:11], v[152:155], v[232:235], v[8:11]
	v_mfma_f32_16x16x32_bf16 v[60:63], v[148:151], v[190:193], v[60:63]
	v_mfma_f32_16x16x32_bf16 v[56:59], v[156:159], v[190:193], v[56:59]
	v_mfma_f32_16x16x32_bf16 v[44:47], v[148:151], v[198:201], v[44:47]
	v_mfma_f32_16x16x32_bf16 v[40:43], v[156:159], v[198:201], v[40:43]
	v_mfma_f32_16x16x32_bf16 v[28:31], v[148:151], v[228:231], v[28:31]
	v_mfma_f32_16x16x32_bf16 v[24:27], v[156:159], v[228:231], v[24:27]
	v_mfma_f32_16x16x32_bf16 v[12:15], v[148:151], v[236:239], v[12:15]
	v_mfma_f32_16x16x32_bf16 v[8:11], v[156:159], v[236:239], v[8:11]
	s_setprio 0
	s_setprio 1
	v_mfma_f32_16x16x32_bf16 v[52:55], v[170:173], v[186:189], v[52:55]
	v_mfma_f32_16x16x32_bf16 v[48:51], v[178:181], v[186:189], v[48:51]
	v_mfma_f32_16x16x32_bf16 v[36:39], v[170:173], v[194:197], v[36:39]
	v_mfma_f32_16x16x32_bf16 v[32:35], v[178:181], v[194:197], v[32:35]
	v_mfma_f32_16x16x32_bf16 v[20:23], v[170:173], v[202:205], v[20:23]
	v_mfma_f32_16x16x32_bf16 v[16:19], v[178:181], v[202:205], v[16:19]
	v_mfma_f32_16x16x32_bf16 v[4:7], v[170:173], v[232:235], v[4:7]
	v_mfma_f32_16x16x32_bf16 v[0:3], v[178:181], v[232:235], v[0:3]
	v_mfma_f32_16x16x32_bf16 v[52:55], v[174:177], v[190:193], v[52:55]
	v_mfma_f32_16x16x32_bf16 v[48:51], v[182:185], v[190:193], v[48:51]
	v_mfma_f32_16x16x32_bf16 v[36:39], v[174:177], v[198:201], v[36:39]
	v_mfma_f32_16x16x32_bf16 v[32:35], v[182:185], v[198:201], v[32:35]
	v_mfma_f32_16x16x32_bf16 v[20:23], v[174:177], v[228:231], v[20:23]
	v_mfma_f32_16x16x32_bf16 v[16:19], v[182:185], v[228:231], v[16:19]
	v_mfma_f32_16x16x32_bf16 v[4:7], v[174:177], v[236:239], v[4:7]
	v_mfma_f32_16x16x32_bf16 v[0:3], v[182:185], v[236:239], v[0:3]
	s_setprio 0
	s_add_i32 s46, s46, 2
	s_add_u32 s44, s44, 0x100
	s_addc_u32 s45, s45, 0
	s_add_u32 s22, s22, 0x100
	s_addc_u32 s23, s23, 0
	s_cmp_gt_u32 s46, 5
	s_barrier
	s_cbranch_scc0 .LBB0_147
	v_readlane_b32 s22, v253, 23
	v_readlane_b32 s23, v253, 24
	s_and_b64 vcc, exec, s[22:23]
	s_cbranch_vccz .LBB0_150
	s_barrier

.LBB0_167:
	s_add_i32 s45, 0, 0x10000
	v_add_u32_e32 v142, s45, v145
	s_add_i32 s48, 0, 0x14000
	ds_read_b128 v[138:141], v142
	ds_read_b128 v[148:151], v142 offset:1024
	ds_read_b128 v[152:155], v142 offset:2048
	ds_read_b128 v[156:159], v142 offset:3072
	v_add_u32_e32 v142, s48, v145
	ds_read_b128 v[170:173], v142
	ds_read_b128 v[174:177], v142 offset:1024
	ds_read_b128 v[178:181], v142 offset:2048
	ds_read_b128 v[182:185], v142 offset:3072
	v_lshl_add_u64 v[142:143], s[20:21], 0, v[136:137]
	s_add_i32 m0, s30, 0xc000
	ds_read_b128 v[186:189], v147
	ds_read_b128 v[190:193], v147 offset:1024
	ds_read_b128 v[194:197], v147 offset:2048
	ds_read_b128 v[198:201], v147 offset:3072
	ds_read_b128 v[202:205], v147 offset:4096
	ds_read_b128 v[228:231], v147 offset:5120
	ds_read_b128 v[232:235], v147 offset:6144
	ds_read_b128 v[236:239], v147 offset:7168
	s_add_u32 s22, s20, 0xfffe0080
	s_addc_u32 s23, s21, -1
	s_cmp_eq_u32 s44, 4
	s_cselect_b32 s25, s15, s23
	s_cselect_b32 s24, s40, s22
	s_cselect_b32 s23, s13, s43
	s_cselect_b32 s22, s41, s42
	global_load_lds_dwordx4 v[142:143], off
	v_lshl_add_u64 v[142:143], s[20:21], 0, v[134:135]
	s_add_i32 m0, s30, 0xe000
	s_nop 0
	global_load_lds_dwordx4 v[142:143], off
	s_waitcnt vmcnt(8)
	s_waitcnt lgkmcnt(0)
	s_barrier
	s_setprio 1
	s_waitcnt lgkmcnt(0)
	v_mfma_f32_16x16x32_bf16 v[124:127], v[138:141], v[186:189], v[124:127]
	v_mfma_f32_16x16x32_bf16 v[120:123], v[152:155], v[186:189], v[120:123]
	v_mfma_f32_16x16x32_bf16 v[108:111], v[138:141], v[194:197], v[108:111]
	v_mfma_f32_16x16x32_bf16 v[104:107], v[152:155], v[194:197], v[104:107]
	v_mfma_f32_16x16x32_bf16 v[92:95], v[138:141], v[202:205], v[92:95]
	v_mfma_f32_16x16x32_bf16 v[88:91], v[152:155], v[202:205], v[88:91]
	v_mfma_f32_16x16x32_bf16 v[76:79], v[138:141], v[232:235], v[76:79]
	v_mfma_f32_16x16x32_bf16 v[72:75], v[152:155], v[232:235], v[72:75]
	v_mfma_f32_16x16x32_bf16 v[124:127], v[148:151], v[190:193], v[124:127]
	v_mfma_f32_16x16x32_bf16 v[120:123], v[156:159], v[190:193], v[120:123]
	v_mfma_f32_16x16x32_bf16 v[108:111], v[148:151], v[198:201], v[108:111]
	v_mfma_f32_16x16x32_bf16 v[104:107], v[156:159], v[198:201], v[104:107]
	v_mfma_f32_16x16x32_bf16 v[92:95], v[148:151], v[228:231], v[92:95]
	v_mfma_f32_16x16x32_bf16 v[88:91], v[156:159], v[228:231], v[88:91]
	v_mfma_f32_16x16x32_bf16 v[76:79], v[148:151], v[236:239], v[76:79]
	v_mfma_f32_16x16x32_bf16 v[72:75], v[156:159], v[236:239], v[72:75]
	s_setprio 0
	s_setprio 1
	v_mfma_f32_16x16x32_bf16 v[116:119], v[170:173], v[186:189], v[116:119]
	v_mfma_f32_16x16x32_bf16 v[112:115], v[178:181], v[186:189], v[112:115]
	v_mfma_f32_16x16x32_bf16 v[100:103], v[170:173], v[194:197], v[100:103]
	v_mfma_f32_16x16x32_bf16 v[96:99], v[178:181], v[194:197], v[96:99]
	v_mfma_f32_16x16x32_bf16 v[84:87], v[170:173], v[202:205], v[84:87]
	v_mfma_f32_16x16x32_bf16 v[80:83], v[178:181], v[202:205], v[80:83]
	v_mfma_f32_16x16x32_bf16 v[68:71], v[170:173], v[232:235], v[68:71]
	v_mfma_f32_16x16x32_bf16 v[64:67], v[178:181], v[232:235], v[64:67]
	v_mfma_f32_16x16x32_bf16 v[116:119], v[174:177], v[190:193], v[116:119]
	v_mfma_f32_16x16x32_bf16 v[112:115], v[182:185], v[190:193], v[112:115]
	v_mfma_f32_16x16x32_bf16 v[100:103], v[174:177], v[198:201], v[100:103]
	v_mfma_f32_16x16x32_bf16 v[96:99], v[182:185], v[198:201], v[96:99]
	v_mfma_f32_16x16x32_bf16 v[84:87], v[174:177], v[228:231], v[84:87]
	v_mfma_f32_16x16x32_bf16 v[80:83], v[182:185], v[228:231], v[80:83]
	v_mfma_f32_16x16x32_bf16 v[68:71], v[174:177], v[236:239], v[68:71]
	v_mfma_f32_16x16x32_bf16 v[64:67], v[182:185], v[236:239], v[64:67]
	s_setprio 0
	s_barrier
	ds_read_b128 v[186:189], v147 offset:16384
	ds_read_b128 v[190:193], v147 offset:17408
	ds_read_b128 v[194:197], v147 offset:18432
	ds_read_b128 v[198:201], v147 offset:19456
	ds_read_b128 v[202:205], v147 offset:20480
	ds_read_b128 v[228:231], v147 offset:21504
	ds_read_b128 v[232:235], v147 offset:22528
	ds_read_b128 v[236:239], v147 offset:23552
	s_add_i32 s45, s45, s77
	s_mov_b32 m0, s45
	v_lshl_add_u64 v[142:143], s[22:23], 0, v[160:161]
	global_load_lds_dwordx4 v[142:143], off
	s_add_i32 m0, s45, 0x2000
	s_add_u32 s46, s22, 0x20000
	v_lshl_add_u64 v[166:167], s[22:23], 0, v[128:129]
	s_addc_u32 s47, s23, 0
	s_add_i32 s45, s48, s77
	global_load_lds_dwordx4 v[166:167], off
	v_lshl_add_u64 v[168:169], s[46:47], 0, v[160:161]
	s_mov_b32 m0, s45
	v_lshl_add_u64 v[206:207], s[24:25], 0, v[130:131]
	global_load_lds_dwordx4 v[168:169], off
	v_lshl_add_u64 v[168:169], s[46:47], 0, v[128:129]
	s_add_i32 m0, s45, 0x2000
	s_nop 0
	global_load_lds_dwordx4 v[168:169], off
	v_lshl_add_u64 v[168:169], s[24:25], 0, v[132:133]
	s_mov_b32 m0, s30
	s_nop 0
	global_load_lds_dwordx4 v[168:169], off
	s_mov_b32 m0, s31
	s_nop 0
	global_load_lds_dwordx4 v[206:207], off
	s_waitcnt vmcnt(8)
	s_waitcnt lgkmcnt(0)
	s_barrier
	s_setprio 1
	s_waitcnt lgkmcnt(0)
	v_mfma_f32_16x16x32_bf16 v[60:63], v[138:141], v[186:189], v[60:63]
	v_mfma_f32_16x16x32_bf16 v[56:59], v[152:155], v[186:189], v[56:59]
	v_mfma_f32_16x16x32_bf16 v[44:47], v[138:141], v[194:197], v[44:47]
	v_mfma_f32_16x16x32_bf16 v[40:43], v[152:155], v[194:197], v[40:43]
	v_mfma_f32_16x16x32_bf16 v[28:31], v[138:141], v[202:205], v[28:31]
	v_mfma_f32_16x16x32_bf16 v[24:27], v[152:155], v[202:205], v[24:27]
	v_mfma_f32_16x16x32_bf16 v[12:15], v[138:141], v[232:235], v[12:15]
	v_mfma_f32_16x16x32_bf16 v[8:11], v[152:155], v[232:235], v[8:11]
	v_mfma_f32_16x16x32_bf16 v[60:63], v[148:151], v[190:193], v[60:63]
	v_mfma_f32_16x16x32_bf16 v[56:59], v[156:159], v[190:193], v[56:59]
	v_mfma_f32_16x16x32_bf16 v[44:47], v[148:151], v[198:201], v[44:47]
	v_mfma_f32_16x16x32_bf16 v[40:43], v[156:159], v[198:201], v[40:43]
	v_mfma_f32_16x16x32_bf16 v[28:31], v[148:151], v[228:231], v[28:31]
	v_mfma_f32_16x16x32_bf16 v[24:27], v[156:159], v[228:231], v[24:27]
	v_mfma_f32_16x16x32_bf16 v[12:15], v[148:151], v[236:239], v[12:15]
	v_mfma_f32_16x16x32_bf16 v[8:11], v[156:159], v[236:239], v[8:11]
	s_setprio 0
	s_setprio 1
	v_mfma_f32_16x16x32_bf16 v[52:55], v[170:173], v[186:189], v[52:55]
	v_mfma_f32_16x16x32_bf16 v[48:51], v[178:181], v[186:189], v[48:51]
	v_mfma_f32_16x16x32_bf16 v[36:39], v[170:173], v[194:197], v[36:39]
	v_mfma_f32_16x16x32_bf16 v[32:35], v[178:181], v[194:197], v[32:35]
	v_mfma_f32_16x16x32_bf16 v[20:23], v[170:173], v[202:205], v[20:23]
	v_mfma_f32_16x16x32_bf16 v[16:19], v[178:181], v[202:205], v[16:19]
	v_mfma_f32_16x16x32_bf16 v[4:7], v[170:173], v[232:235], v[4:7]
	v_mfma_f32_16x16x32_bf16 v[0:3], v[178:181], v[232:235], v[0:3]
	v_mfma_f32_16x16x32_bf16 v[52:55], v[174:177], v[190:193], v[52:55]
	v_mfma_f32_16x16x32_bf16 v[48:51], v[182:185], v[190:193], v[48:51]
	v_mfma_f32_16x16x32_bf16 v[36:39], v[174:177], v[198:201], v[36:39]
	v_mfma_f32_16x16x32_bf16 v[32:35], v[182:185], v[198:201], v[32:35]
	v_mfma_f32_16x16x32_bf16 v[20:23], v[174:177], v[228:231], v[20:23]
	v_mfma_f32_16x16x32_bf16 v[16:19], v[182:185], v[228:231], v[16:19]
	v_mfma_f32_16x16x32_bf16 v[4:7], v[174:177], v[236:239], v[4:7]
	v_mfma_f32_16x16x32_bf16 v[0:3], v[182:185], v[236:239], v[0:3]
	s_setprio 0
	s_barrier
	s_add_i32 s45, 0, 0x18000
	s_add_i32 s46, 0, 0x1c000
	v_add_u32_e32 v156, s45, v145
	v_add_u32_e32 v182, s46, v145
	ds_read_b128 v[138:141], v156
	ds_read_b128 v[148:151], v156 offset:1024
	ds_read_b128 v[152:155], v156 offset:2048
	ds_read_b128 v[156:159], v156 offset:3072
	ds_read_b128 v[170:173], v182
	ds_read_b128 v[174:177], v182 offset:1024
	ds_read_b128 v[178:181], v182 offset:2048
	ds_read_b128 v[182:185], v182 offset:3072
	s_add_u32 s24, s24, 0x20000
	s_addc_u32 s25, s25, 0
	s_mov_b32 m0, s34
	v_lshl_add_u64 v[240:241], s[24:25], 0, v[132:133]
	ds_read_b128 v[186:189], v147 offset:32768
	ds_read_b128 v[190:193], v147 offset:33792
	ds_read_b128 v[194:197], v147 offset:34816
	ds_read_b128 v[198:201], v147 offset:35840
	ds_read_b128 v[202:205], v147 offset:36864
	ds_read_b128 v[228:231], v147 offset:37888
	ds_read_b128 v[232:235], v147 offset:38912
	ds_read_b128 v[236:239], v147 offset:39936
	global_load_lds_dwordx4 v[240:241], off
	v_lshl_add_u64 v[240:241], s[24:25], 0, v[130:131]
	s_mov_b32 m0, s35
	s_nop 0
	global_load_lds_dwordx4 v[240:241], off
	s_waitcnt vmcnt(8)
	s_waitcnt lgkmcnt(0)
	s_barrier
	s_setprio 1
	s_waitcnt lgkmcnt(0)
	v_mfma_f32_16x16x32_bf16 v[124:127], v[138:141], v[186:189], v[124:127]
	v_mfma_f32_16x16x32_bf16 v[120:123], v[152:155], v[186:189], v[120:123]
	v_mfma_f32_16x16x32_bf16 v[108:111], v[138:141], v[194:197], v[108:111]
	v_mfma_f32_16x16x32_bf16 v[104:107], v[152:155], v[194:197], v[104:107]
	v_mfma_f32_16x16x32_bf16 v[92:95], v[138:141], v[202:205], v[92:95]
	v_mfma_f32_16x16x32_bf16 v[88:91], v[152:155], v[202:205], v[88:91]
	v_mfma_f32_16x16x32_bf16 v[76:79], v[138:141], v[232:235], v[76:79]
	v_mfma_f32_16x16x32_bf16 v[72:75], v[152:155], v[232:235], v[72:75]
	v_mfma_f32_16x16x32_bf16 v[124:127], v[148:151], v[190:193], v[124:127]
	v_mfma_f32_16x16x32_bf16 v[120:123], v[156:159], v[190:193], v[120:123]
	v_mfma_f32_16x16x32_bf16 v[108:111], v[148:151], v[198:201], v[108:111]
	v_mfma_f32_16x16x32_bf16 v[104:107], v[156:159], v[198:201], v[104:107]
	v_mfma_f32_16x16x32_bf16 v[92:95], v[148:151], v[228:231], v[92:95]
	v_mfma_f32_16x16x32_bf16 v[88:91], v[156:159], v[228:231], v[88:91]
	v_mfma_f32_16x16x32_bf16 v[76:79], v[148:151], v[236:239], v[76:79]
	v_mfma_f32_16x16x32_bf16 v[72:75], v[156:159], v[236:239], v[72:75]
	s_setprio 0
	s_setprio 1
	v_mfma_f32_16x16x32_bf16 v[116:119], v[170:173], v[186:189], v[116:119]
	v_mfma_f32_16x16x32_bf16 v[112:115], v[178:181], v[186:189], v[112:115]
	v_mfma_f32_16x16x32_bf16 v[100:103], v[170:173], v[194:197], v[100:103]
	v_mfma_f32_16x16x32_bf16 v[96:99], v[178:181], v[194:197], v[96:99]
	v_mfma_f32_16x16x32_bf16 v[84:87], v[170:173], v[202:205], v[84:87]
	v_mfma_f32_16x16x32_bf16 v[80:83], v[178:181], v[202:205], v[80:83]
	v_mfma_f32_16x16x32_bf16 v[68:71], v[170:173], v[232:235], v[68:71]
	v_mfma_f32_16x16x32_bf16 v[64:67], v[178:181], v[232:235], v[64:67]
	v_mfma_f32_16x16x32_bf16 v[116:119], v[174:177], v[190:193], v[116:119]
	v_mfma_f32_16x16x32_bf16 v[112:115], v[182:185], v[190:193], v[112:115]
	v_mfma_f32_16x16x32_bf16 v[100:103], v[174:177], v[198:201], v[100:103]
	v_mfma_f32_16x16x32_bf16 v[96:99], v[182:185], v[198:201], v[96:99]
	v_mfma_f32_16x16x32_bf16 v[84:87], v[174:177], v[228:231], v[84:87]
	v_mfma_f32_16x16x32_bf16 v[80:83], v[182:185], v[228:231], v[80:83]
	v_mfma_f32_16x16x32_bf16 v[68:71], v[174:177], v[236:239], v[68:71]
	v_mfma_f32_16x16x32_bf16 v[64:67], v[182:185], v[236:239], v[64:67]
	s_setprio 0
	s_barrier
	ds_read_b128 v[186:189], v147 offset:49152
	ds_read_b128 v[190:193], v147 offset:50176
	ds_read_b128 v[194:197], v147 offset:51200
	ds_read_b128 v[198:201], v147 offset:52224
	ds_read_b128 v[202:205], v147 offset:53248
	ds_read_b128 v[228:231], v147 offset:54272
	ds_read_b128 v[232:235], v147 offset:55296
	ds_read_b128 v[236:239], v147 offset:56320
	s_add_i32 s24, s45, s77
	s_mov_b32 m0, s24
	v_lshl_add_u64 v[142:143], v[142:143], 0, s[96:97]
	global_load_lds_dwordx4 v[142:143], off
	s_add_i32 m0, s24, 0x2000
	s_add_u32 s22, s22, 0x20080
	v_lshl_add_u64 v[142:143], v[166:167], 0, s[96:97]
	s_addc_u32 s23, s23, 0
	s_add_i32 s24, s46, s77
	global_load_lds_dwordx4 v[142:143], off
	v_lshl_add_u64 v[142:143], s[22:23], 0, v[160:161]
	s_mov_b32 m0, s24
	s_nop 0
	global_load_lds_dwordx4 v[142:143], off
	v_lshl_add_u64 v[142:143], s[22:23], 0, v[128:129]
	s_add_i32 m0, s24, 0x2000
	s_nop 0
	global_load_lds_dwordx4 v[142:143], off
	v_lshl_add_u64 v[142:143], v[168:169], 0, s[96:97]
	s_mov_b32 m0, s36
	s_nop 0
	global_load_lds_dwordx4 v[142:143], off
	v_lshl_add_u64 v[142:143], v[206:207], 0, s[96:97]
	s_mov_b32 m0, s37
	s_nop 0
	global_load_lds_dwordx4 v[142:143], off
	s_waitcnt vmcnt(8)
	s_waitcnt lgkmcnt(0)
	s_barrier
	s_setprio 1
	s_waitcnt lgkmcnt(0)
	v_mfma_f32_16x16x32_bf16 v[60:63], v[138:141], v[186:189], v[60:63]
	v_mfma_f32_16x16x32_bf16 v[56:59], v[152:155], v[186:189], v[56:59]
	v_mfma_f32_16x16x32_bf16 v[44:47], v[138:141], v[194:197], v[44:47]
	v_mfma_f32_16x16x32_bf16 v[40:43], v[152:155], v[194:197], v[40:43]
	v_mfma_f32_16x16x32_bf16 v[28:31], v[138:141], v[202:205], v[28:31]
	v_mfma_f32_16x16x32_bf16 v[24:27], v[152:155], v[202:205], v[24:27]
	v_mfma_f32_16x16x32_bf16 v[12:15], v[138:141], v[232:235], v[12:15]
	v_mfma_f32_16x16x32_bf16 v[8:11], v[152:155], v[232:235], v[8:11]
	v_mfma_f32_16x16x32_bf16 v[60:63], v[148:151], v[190:193], v[60:63]
	v_mfma_f32_16x16x32_bf16 v[56:59], v[156:159], v[190:193], v[56:59]
	v_mfma_f32_16x16x32_bf16 v[44:47], v[148:151], v[198:201], v[44:47]
	v_mfma_f32_16x16x32_bf16 v[40:43], v[156:159], v[198:201], v[40:43]
	v_mfma_f32_16x16x32_bf16 v[28:31], v[148:151], v[228:231], v[28:31]
	v_mfma_f32_16x16x32_bf16 v[24:27], v[156:159], v[228:231], v[24:27]
	v_mfma_f32_16x16x32_bf16 v[12:15], v[148:151], v[236:239], v[12:15]
	v_mfma_f32_16x16x32_bf16 v[8:11], v[156:159], v[236:239], v[8:11]
	s_setprio 0
	s_setprio 1
	v_mfma_f32_16x16x32_bf16 v[52:55], v[170:173], v[186:189], v[52:55]
	v_mfma_f32_16x16x32_bf16 v[48:51], v[178:181], v[186:189], v[48:51]
	v_mfma_f32_16x16x32_bf16 v[36:39], v[170:173], v[194:197], v[36:39]
	v_mfma_f32_16x16x32_bf16 v[32:35], v[178:181], v[194:197], v[32:35]
	v_mfma_f32_16x16x32_bf16 v[20:23], v[170:173], v[202:205], v[20:23]
	v_mfma_f32_16x16x32_bf16 v[16:19], v[178:181], v[202:205], v[16:19]
	v_mfma_f32_16x16x32_bf16 v[4:7], v[170:173], v[232:235], v[4:7]
	v_mfma_f32_16x16x32_bf16 v[0:3], v[178:181], v[232:235], v[0:3]
	v_mfma_f32_16x16x32_bf16 v[52:55], v[174:177], v[190:193], v[52:55]
	v_mfma_f32_16x16x32_bf16 v[48:51], v[182:185], v[190:193], v[48:51]
	v_mfma_f32_16x16x32_bf16 v[36:39], v[174:177], v[198:201], v[36:39]
	v_mfma_f32_16x16x32_bf16 v[32:35], v[182:185], v[198:201], v[32:35]
	v_mfma_f32_16x16x32_bf16 v[20:23], v[174:177], v[228:231], v[20:23]
	v_mfma_f32_16x16x32_bf16 v[16:19], v[182:185], v[228:231], v[16:19]
	v_mfma_f32_16x16x32_bf16 v[4:7], v[174:177], v[236:239], v[4:7]
	v_mfma_f32_16x16x32_bf16 v[0:3], v[182:185], v[236:239], v[0:3]
	s_setprio 0
	s_add_i32 s44, s44, 2
	s_add_u32 s42, s42, 0x100
	s_addc_u32 s43, s43, 0
	s_add_u32 s20, s20, 0x100
	s_addc_u32 s21, s21, 0
	s_cmp_gt_u32 s44, 5
	s_barrier
	s_cbranch_scc0 .LBB0_167
	v_readlane_b32 s20, v253, 23
	v_readlane_b32 s21, v253, 24
	s_and_b64 vcc, exec, s[20:21]
	s_cbranch_vccz .LBB0_170
	s_barrier

.LBB0_272:
	s_add_i32 s43, 0, 0x10000
	v_add_u32_e32 v147, s43, v145
	s_add_i32 s46, 0, 0x14000
	ds_read_b128 v[140:143], v147
	ds_read_b128 v[148:151], v147 offset:1024
	ds_read_b128 v[152:155], v147 offset:2048
	ds_read_b128 v[156:159], v147 offset:3072
	v_add_u32_e32 v147, s46, v145
	ds_read_b128 v[170:173], v147
	ds_read_b128 v[174:177], v147 offset:1024
	ds_read_b128 v[178:181], v147 offset:2048
	ds_read_b128 v[182:185], v147 offset:3072
	v_lshl_add_u64 v[166:167], s[14:15], 0, v[138:139]
	s_add_i32 m0, s23, 0xc000
	ds_read_b128 v[186:189], v146
	ds_read_b128 v[190:193], v146 offset:1024
	ds_read_b128 v[194:197], v146 offset:2048
	ds_read_b128 v[198:201], v146 offset:3072
	ds_read_b128 v[202:205], v146 offset:4096
	ds_read_b128 v[228:231], v146 offset:5120
	ds_read_b128 v[232:235], v146 offset:6144
	ds_read_b128 v[236:239], v146 offset:7168
	s_add_u32 s16, s14, 0xfffc0080
	s_addc_u32 s17, s15, -1
	s_cmp_eq_u32 s42, 12
	s_cselect_b32 s19, s9, s17
	s_cselect_b32 s18, s38, s16
	s_cselect_b32 s17, s1, s41
	s_cselect_b32 s16, s39, s40
	global_load_lds_dwordx4 v[166:167], off
	v_lshl_add_u64 v[166:167], s[14:15], 0, v[136:137]
	s_add_i32 m0, s23, 0xe000
	s_nop 0
	global_load_lds_dwordx4 v[166:167], off
	s_waitcnt vmcnt(8)
	s_waitcnt lgkmcnt(0)
	s_barrier
	s_setprio 1
	s_waitcnt lgkmcnt(0)
	v_mfma_f32_16x16x32_bf16 v[124:127], v[140:143], v[186:189], v[124:127]
	v_mfma_f32_16x16x32_bf16 v[120:123], v[152:155], v[186:189], v[120:123]
	v_mfma_f32_16x16x32_bf16 v[108:111], v[140:143], v[194:197], v[108:111]
	v_mfma_f32_16x16x32_bf16 v[104:107], v[152:155], v[194:197], v[104:107]
	v_mfma_f32_16x16x32_bf16 v[92:95], v[140:143], v[202:205], v[92:95]
	v_mfma_f32_16x16x32_bf16 v[88:91], v[152:155], v[202:205], v[88:91]
	v_mfma_f32_16x16x32_bf16 v[76:79], v[140:143], v[232:235], v[76:79]
	v_mfma_f32_16x16x32_bf16 v[72:75], v[152:155], v[232:235], v[72:75]
	v_mfma_f32_16x16x32_bf16 v[124:127], v[148:151], v[190:193], v[124:127]
	v_mfma_f32_16x16x32_bf16 v[120:123], v[156:159], v[190:193], v[120:123]
	v_mfma_f32_16x16x32_bf16 v[108:111], v[148:151], v[198:201], v[108:111]
	v_mfma_f32_16x16x32_bf16 v[104:107], v[156:159], v[198:201], v[104:107]
	v_mfma_f32_16x16x32_bf16 v[92:95], v[148:151], v[228:231], v[92:95]
	v_mfma_f32_16x16x32_bf16 v[88:91], v[156:159], v[228:231], v[88:91]
	v_mfma_f32_16x16x32_bf16 v[76:79], v[148:151], v[236:239], v[76:79]
	v_mfma_f32_16x16x32_bf16 v[72:75], v[156:159], v[236:239], v[72:75]
	s_setprio 0
	s_setprio 1
	v_mfma_f32_16x16x32_bf16 v[116:119], v[170:173], v[186:189], v[116:119]
	v_mfma_f32_16x16x32_bf16 v[112:115], v[178:181], v[186:189], v[112:115]
	v_mfma_f32_16x16x32_bf16 v[100:103], v[170:173], v[194:197], v[100:103]
	v_mfma_f32_16x16x32_bf16 v[96:99], v[178:181], v[194:197], v[96:99]
	v_mfma_f32_16x16x32_bf16 v[84:87], v[170:173], v[202:205], v[84:87]
	v_mfma_f32_16x16x32_bf16 v[80:83], v[178:181], v[202:205], v[80:83]
	v_mfma_f32_16x16x32_bf16 v[68:71], v[170:173], v[232:235], v[68:71]
	v_mfma_f32_16x16x32_bf16 v[64:67], v[178:181], v[232:235], v[64:67]
	v_mfma_f32_16x16x32_bf16 v[116:119], v[174:177], v[190:193], v[116:119]
	v_mfma_f32_16x16x32_bf16 v[112:115], v[182:185], v[190:193], v[112:115]
	v_mfma_f32_16x16x32_bf16 v[100:103], v[174:177], v[198:201], v[100:103]
	v_mfma_f32_16x16x32_bf16 v[96:99], v[182:185], v[198:201], v[96:99]
	v_mfma_f32_16x16x32_bf16 v[84:87], v[174:177], v[228:231], v[84:87]
	v_mfma_f32_16x16x32_bf16 v[80:83], v[182:185], v[228:231], v[80:83]
	v_mfma_f32_16x16x32_bf16 v[68:71], v[174:177], v[236:239], v[68:71]
	v_mfma_f32_16x16x32_bf16 v[64:67], v[182:185], v[236:239], v[64:67]
	s_setprio 0
	s_barrier
	ds_read_b128 v[186:189], v146 offset:16384
	ds_read_b128 v[190:193], v146 offset:17408
	ds_read_b128 v[194:197], v146 offset:18432
	ds_read_b128 v[198:201], v146 offset:19456
	ds_read_b128 v[202:205], v146 offset:20480
	ds_read_b128 v[228:231], v146 offset:21504
	ds_read_b128 v[232:235], v146 offset:22528
	ds_read_b128 v[236:239], v146 offset:23552
	s_add_i32 s43, s43, s77
	s_mov_b32 m0, s43
	v_lshl_add_u64 v[166:167], s[16:17], 0, v[160:161]
	global_load_lds_dwordx4 v[166:167], off
	s_add_i32 m0, s43, 0x2000
	s_add_u32 s44, s16, 0x40000
	v_lshl_add_u64 v[168:169], s[16:17], 0, v[128:129]
	s_addc_u32 s45, s17, 0
	s_add_i32 s43, s46, s77
	global_load_lds_dwordx4 v[168:169], off
	v_lshl_add_u64 v[206:207], s[44:45], 0, v[160:161]
	s_mov_b32 m0, s43
	v_lshl_add_u64 v[240:241], s[18:19], 0, v[130:131]
	global_load_lds_dwordx4 v[206:207], off
	v_lshl_add_u64 v[206:207], s[44:45], 0, v[128:129]
	s_add_i32 m0, s43, 0x2000
	s_nop 0
	global_load_lds_dwordx4 v[206:207], off
	v_lshl_add_u64 v[206:207], s[18:19], 0, v[132:133]
	s_mov_b32 m0, s23
	s_nop 0
	global_load_lds_dwordx4 v[206:207], off
	s_mov_b32 m0, s24
	s_nop 0
	global_load_lds_dwordx4 v[240:241], off
	s_waitcnt vmcnt(8)
	s_waitcnt lgkmcnt(0)
	s_barrier
	s_setprio 1
	s_waitcnt lgkmcnt(0)
	v_mfma_f32_16x16x32_bf16 v[60:63], v[140:143], v[186:189], v[60:63]
	v_mfma_f32_16x16x32_bf16 v[56:59], v[152:155], v[186:189], v[56:59]
	v_mfma_f32_16x16x32_bf16 v[44:47], v[140:143], v[194:197], v[44:47]
	v_mfma_f32_16x16x32_bf16 v[40:43], v[152:155], v[194:197], v[40:43]
	v_mfma_f32_16x16x32_bf16 v[28:31], v[140:143], v[202:205], v[28:31]
	v_mfma_f32_16x16x32_bf16 v[24:27], v[152:155], v[202:205], v[24:27]
	v_mfma_f32_16x16x32_bf16 v[12:15], v[140:143], v[232:235], v[12:15]
	v_mfma_f32_16x16x32_bf16 v[8:11], v[152:155], v[232:235], v[8:11]
	v_mfma_f32_16x16x32_bf16 v[60:63], v[148:151], v[190:193], v[60:63]
	v_mfma_f32_16x16x32_bf16 v[56:59], v[156:159], v[190:193], v[56:59]
	v_mfma_f32_16x16x32_bf16 v[44:47], v[148:151], v[198:201], v[44:47]
	v_mfma_f32_16x16x32_bf16 v[40:43], v[156:159], v[198:201], v[40:43]
	v_mfma_f32_16x16x32_bf16 v[28:31], v[148:151], v[228:231], v[28:31]
	v_mfma_f32_16x16x32_bf16 v[24:27], v[156:159], v[228:231], v[24:27]
	v_mfma_f32_16x16x32_bf16 v[12:15], v[148:151], v[236:239], v[12:15]
	v_mfma_f32_16x16x32_bf16 v[8:11], v[156:159], v[236:239], v[8:11]
	s_setprio 0
	s_setprio 1
	v_mfma_f32_16x16x32_bf16 v[52:55], v[170:173], v[186:189], v[52:55]
	v_mfma_f32_16x16x32_bf16 v[48:51], v[178:181], v[186:189], v[48:51]
	v_mfma_f32_16x16x32_bf16 v[36:39], v[170:173], v[194:197], v[36:39]
	v_mfma_f32_16x16x32_bf16 v[32:35], v[178:181], v[194:197], v[32:35]
	v_mfma_f32_16x16x32_bf16 v[20:23], v[170:173], v[202:205], v[20:23]
	v_mfma_f32_16x16x32_bf16 v[16:19], v[178:181], v[202:205], v[16:19]
	v_mfma_f32_16x16x32_bf16 v[4:7], v[170:173], v[232:235], v[4:7]
	v_mfma_f32_16x16x32_bf16 v[0:3], v[178:181], v[232:235], v[0:3]
	v_mfma_f32_16x16x32_bf16 v[52:55], v[174:177], v[190:193], v[52:55]
	v_mfma_f32_16x16x32_bf16 v[48:51], v[182:185], v[190:193], v[48:51]
	v_mfma_f32_16x16x32_bf16 v[36:39], v[174:177], v[198:201], v[36:39]
	v_mfma_f32_16x16x32_bf16 v[32:35], v[182:185], v[198:201], v[32:35]
	v_mfma_f32_16x16x32_bf16 v[20:23], v[174:177], v[228:231], v[20:23]
	v_mfma_f32_16x16x32_bf16 v[16:19], v[182:185], v[228:231], v[16:19]
	v_mfma_f32_16x16x32_bf16 v[4:7], v[174:177], v[236:239], v[4:7]
	v_mfma_f32_16x16x32_bf16 v[0:3], v[182:185], v[236:239], v[0:3]
	s_setprio 0
	s_barrier
	s_add_i32 s43, 0, 0x18000
	v_add_u32_e32 v147, s43, v145
	s_add_i32 s44, 0, 0x1c000
	ds_read_b128 v[140:143], v147
	ds_read_b128 v[148:151], v147 offset:1024
	ds_read_b128 v[152:155], v147 offset:2048
	ds_read_b128 v[156:159], v147 offset:3072
	v_add_u32_e32 v147, s44, v145
	ds_read_b128 v[170:173], v147
	ds_read_b128 v[174:177], v147 offset:1024
	ds_read_b128 v[178:181], v147 offset:2048
	ds_read_b128 v[182:185], v147 offset:3072
	s_add_u32 s18, s18, 0x40000
	s_addc_u32 s19, s19, 0
	s_mov_b32 m0, s25
	v_lshl_add_u64 v[242:243], s[18:19], 0, v[132:133]
	ds_read_b128 v[186:189], v146 offset:32768
	ds_read_b128 v[190:193], v146 offset:33792
	ds_read_b128 v[194:197], v146 offset:34816
	ds_read_b128 v[198:201], v146 offset:35840
	ds_read_b128 v[202:205], v146 offset:36864
	ds_read_b128 v[228:231], v146 offset:37888
	ds_read_b128 v[232:235], v146 offset:38912
	ds_read_b128 v[236:239], v146 offset:39936
	global_load_lds_dwordx4 v[242:243], off
	v_lshl_add_u64 v[242:243], s[18:19], 0, v[130:131]
	s_mov_b32 m0, s26
	s_nop 0
	global_load_lds_dwordx4 v[242:243], off
	s_waitcnt vmcnt(8)
	s_waitcnt lgkmcnt(0)
	s_barrier
	s_setprio 1
	s_waitcnt lgkmcnt(0)
	v_mfma_f32_16x16x32_bf16 v[124:127], v[140:143], v[186:189], v[124:127]
	v_mfma_f32_16x16x32_bf16 v[120:123], v[152:155], v[186:189], v[120:123]
	v_mfma_f32_16x16x32_bf16 v[108:111], v[140:143], v[194:197], v[108:111]
	v_mfma_f32_16x16x32_bf16 v[104:107], v[152:155], v[194:197], v[104:107]
	v_mfma_f32_16x16x32_bf16 v[92:95], v[140:143], v[202:205], v[92:95]
	v_mfma_f32_16x16x32_bf16 v[88:91], v[152:155], v[202:205], v[88:91]
	v_mfma_f32_16x16x32_bf16 v[76:79], v[140:143], v[232:235], v[76:79]
	v_mfma_f32_16x16x32_bf16 v[72:75], v[152:155], v[232:235], v[72:75]
	v_mfma_f32_16x16x32_bf16 v[124:127], v[148:151], v[190:193], v[124:127]
	v_mfma_f32_16x16x32_bf16 v[120:123], v[156:159], v[190:193], v[120:123]
	v_mfma_f32_16x16x32_bf16 v[108:111], v[148:151], v[198:201], v[108:111]
	v_mfma_f32_16x16x32_bf16 v[104:107], v[156:159], v[198:201], v[104:107]
	v_mfma_f32_16x16x32_bf16 v[92:95], v[148:151], v[228:231], v[92:95]
	v_mfma_f32_16x16x32_bf16 v[88:91], v[156:159], v[228:231], v[88:91]
	v_mfma_f32_16x16x32_bf16 v[76:79], v[148:151], v[236:239], v[76:79]
	v_mfma_f32_16x16x32_bf16 v[72:75], v[156:159], v[236:239], v[72:75]
	s_setprio 0
	s_setprio 1
	v_mfma_f32_16x16x32_bf16 v[116:119], v[170:173], v[186:189], v[116:119]
	v_mfma_f32_16x16x32_bf16 v[112:115], v[178:181], v[186:189], v[112:115]
	v_mfma_f32_16x16x32_bf16 v[100:103], v[170:173], v[194:197], v[100:103]
	v_mfma_f32_16x16x32_bf16 v[96:99], v[178:181], v[194:197], v[96:99]
	v_mfma_f32_16x16x32_bf16 v[84:87], v[170:173], v[202:205], v[84:87]
	v_mfma_f32_16x16x32_bf16 v[80:83], v[178:181], v[202:205], v[80:83]
	v_mfma_f32_16x16x32_bf16 v[68:71], v[170:173], v[232:235], v[68:71]
	v_mfma_f32_16x16x32_bf16 v[64:67], v[178:181], v[232:235], v[64:67]
	v_mfma_f32_16x16x32_bf16 v[116:119], v[174:177], v[190:193], v[116:119]
	v_mfma_f32_16x16x32_bf16 v[112:115], v[182:185], v[190:193], v[112:115]
	v_mfma_f32_16x16x32_bf16 v[100:103], v[174:177], v[198:201], v[100:103]
	v_mfma_f32_16x16x32_bf16 v[96:99], v[182:185], v[198:201], v[96:99]
	v_mfma_f32_16x16x32_bf16 v[84:87], v[174:177], v[228:231], v[84:87]
	v_mfma_f32_16x16x32_bf16 v[80:83], v[182:185], v[228:231], v[80:83]
	v_mfma_f32_16x16x32_bf16 v[68:71], v[174:177], v[236:239], v[68:71]
	v_mfma_f32_16x16x32_bf16 v[64:67], v[182:185], v[236:239], v[64:67]
	s_setprio 0
	s_barrier
	ds_read_b128 v[186:189], v146 offset:49152
	ds_read_b128 v[190:193], v146 offset:50176
	ds_read_b128 v[194:197], v146 offset:51200
	ds_read_b128 v[198:201], v146 offset:52224
	ds_read_b128 v[202:205], v146 offset:53248
	ds_read_b128 v[228:231], v146 offset:54272
	ds_read_b128 v[232:235], v146 offset:55296
	ds_read_b128 v[236:239], v146 offset:56320
	s_add_i32 s18, s43, s77
	s_mov_b32 m0, s18
	v_lshl_add_u64 v[166:167], v[166:167], 0, s[96:97]
	global_load_lds_dwordx4 v[166:167], off
	s_add_i32 m0, s18, 0x2000
	s_add_u32 s16, s16, 0x40080
	v_lshl_add_u64 v[166:167], v[168:169], 0, s[96:97]
	s_addc_u32 s17, s17, 0
	s_add_i32 s18, s44, s77
	global_load_lds_dwordx4 v[166:167], off
	v_lshl_add_u64 v[166:167], s[16:17], 0, v[160:161]
	s_mov_b32 m0, s18
	s_nop 0
	global_load_lds_dwordx4 v[166:167], off
	v_lshl_add_u64 v[166:167], s[16:17], 0, v[128:129]
	s_add_i32 m0, s18, 0x2000
	s_nop 0
	global_load_lds_dwordx4 v[166:167], off
	v_lshl_add_u64 v[166:167], v[206:207], 0, s[96:97]
	s_mov_b32 m0, s31
	s_nop 0
	global_load_lds_dwordx4 v[166:167], off
	v_lshl_add_u64 v[166:167], v[240:241], 0, s[96:97]
	s_mov_b32 m0, s34
	s_nop 0
	global_load_lds_dwordx4 v[166:167], off
	s_waitcnt vmcnt(8)
	s_waitcnt lgkmcnt(0)
	s_barrier
	s_setprio 1
	s_waitcnt lgkmcnt(0)
	v_mfma_f32_16x16x32_bf16 v[60:63], v[140:143], v[186:189], v[60:63]
	v_mfma_f32_16x16x32_bf16 v[56:59], v[152:155], v[186:189], v[56:59]
	v_mfma_f32_16x16x32_bf16 v[44:47], v[140:143], v[194:197], v[44:47]
	v_mfma_f32_16x16x32_bf16 v[40:43], v[152:155], v[194:197], v[40:43]
	v_mfma_f32_16x16x32_bf16 v[28:31], v[140:143], v[202:205], v[28:31]
	v_mfma_f32_16x16x32_bf16 v[24:27], v[152:155], v[202:205], v[24:27]
	v_mfma_f32_16x16x32_bf16 v[12:15], v[140:143], v[232:235], v[12:15]
	v_mfma_f32_16x16x32_bf16 v[8:11], v[152:155], v[232:235], v[8:11]
	v_mfma_f32_16x16x32_bf16 v[60:63], v[148:151], v[190:193], v[60:63]
	v_mfma_f32_16x16x32_bf16 v[56:59], v[156:159], v[190:193], v[56:59]
	v_mfma_f32_16x16x32_bf16 v[44:47], v[148:151], v[198:201], v[44:47]
	v_mfma_f32_16x16x32_bf16 v[40:43], v[156:159], v[198:201], v[40:43]
	v_mfma_f32_16x16x32_bf16 v[28:31], v[148:151], v[228:231], v[28:31]
	v_mfma_f32_16x16x32_bf16 v[24:27], v[156:159], v[228:231], v[24:27]
	v_mfma_f32_16x16x32_bf16 v[12:15], v[148:151], v[236:239], v[12:15]
	v_mfma_f32_16x16x32_bf16 v[8:11], v[156:159], v[236:239], v[8:11]
	s_setprio 0
	s_setprio 1
	v_mfma_f32_16x16x32_bf16 v[52:55], v[170:173], v[186:189], v[52:55]
	v_mfma_f32_16x16x32_bf16 v[48:51], v[178:181], v[186:189], v[48:51]
	v_mfma_f32_16x16x32_bf16 v[36:39], v[170:173], v[194:197], v[36:39]
	v_mfma_f32_16x16x32_bf16 v[32:35], v[178:181], v[194:197], v[32:35]
	v_mfma_f32_16x16x32_bf16 v[20:23], v[170:173], v[202:205], v[20:23]
	v_mfma_f32_16x16x32_bf16 v[16:19], v[178:181], v[202:205], v[16:19]
	v_mfma_f32_16x16x32_bf16 v[4:7], v[170:173], v[232:235], v[4:7]
	v_mfma_f32_16x16x32_bf16 v[0:3], v[178:181], v[232:235], v[0:3]
	v_mfma_f32_16x16x32_bf16 v[52:55], v[174:177], v[190:193], v[52:55]
	v_mfma_f32_16x16x32_bf16 v[48:51], v[182:185], v[190:193], v[48:51]
	v_mfma_f32_16x16x32_bf16 v[36:39], v[174:177], v[198:201], v[36:39]
	v_mfma_f32_16x16x32_bf16 v[32:35], v[182:185], v[198:201], v[32:35]
	v_mfma_f32_16x16x32_bf16 v[20:23], v[174:177], v[228:231], v[20:23]
	v_mfma_f32_16x16x32_bf16 v[16:19], v[182:185], v[228:231], v[16:19]
	v_mfma_f32_16x16x32_bf16 v[4:7], v[174:177], v[236:239], v[4:7]
	v_mfma_f32_16x16x32_bf16 v[0:3], v[182:185], v[236:239], v[0:3]
	s_setprio 0
	s_add_i32 s42, s42, 2
	s_add_u32 s40, s40, 0x100
	s_addc_u32 s41, s41, 0
	s_add_u32 s14, s14, 0x100
	s_addc_u32 s15, s15, 0
	s_cmp_gt_u32 s42, 13
	s_barrier
	s_cbranch_scc0 .LBB0_272
	v_readlane_b32 s14, v253, 23
	v_readlane_b32 s15, v253, 24
	s_and_b64 vcc, exec, s[14:15]
	s_cbranch_vccz .LBB0_275
	s_barrier

.LBB0_290:
	s_add_i32 s42, 0, 0x10000
	v_add_u32_e32 v147, s42, v145
	s_add_i32 s44, 0, 0x14000
	ds_read_b128 v[140:143], v147
	ds_read_b128 v[148:151], v147 offset:1024
	ds_read_b128 v[152:155], v147 offset:2048
	ds_read_b128 v[156:159], v147 offset:3072
	v_add_u32_e32 v147, s44, v145
	ds_read_b128 v[170:173], v147
	ds_read_b128 v[174:177], v147 offset:1024
	ds_read_b128 v[178:181], v147 offset:2048
	ds_read_b128 v[182:185], v147 offset:3072
	v_lshl_add_u64 v[166:167], s[14:15], 0, v[138:139]
	s_add_i32 m0, s23, 0xc000
	ds_read_b128 v[186:189], v146
	ds_read_b128 v[190:193], v146 offset:1024
	ds_read_b128 v[194:197], v146 offset:2048
	ds_read_b128 v[198:201], v146 offset:3072
	ds_read_b128 v[202:205], v146 offset:4096
	ds_read_b128 v[228:231], v146 offset:5120
	ds_read_b128 v[232:235], v146 offset:6144
	ds_read_b128 v[236:239], v146 offset:7168
	s_add_u32 s16, s14, 0xfffc0080
	s_addc_u32 s17, s15, -1
	s_cmp_eq_u32 s41, 12
	s_cselect_b32 s19, s1, s17
	s_cselect_b32 s18, s37, s16
	s_cselect_b32 s17, s9, s40
	s_cselect_b32 s16, s38, s39
	global_load_lds_dwordx4 v[166:167], off
	v_lshl_add_u64 v[166:167], s[14:15], 0, v[136:137]
	s_add_i32 m0, s23, 0xe000
	s_nop 0
	global_load_lds_dwordx4 v[166:167], off
	s_waitcnt vmcnt(8)
	s_waitcnt lgkmcnt(0)
	s_barrier
	s_setprio 1
	s_waitcnt lgkmcnt(0)
	v_mfma_f32_16x16x32_bf16 v[124:127], v[140:143], v[186:189], v[124:127]
	v_mfma_f32_16x16x32_bf16 v[120:123], v[152:155], v[186:189], v[120:123]
	v_mfma_f32_16x16x32_bf16 v[108:111], v[140:143], v[194:197], v[108:111]
	v_mfma_f32_16x16x32_bf16 v[104:107], v[152:155], v[194:197], v[104:107]
	v_mfma_f32_16x16x32_bf16 v[92:95], v[140:143], v[202:205], v[92:95]
	v_mfma_f32_16x16x32_bf16 v[88:91], v[152:155], v[202:205], v[88:91]
	v_mfma_f32_16x16x32_bf16 v[76:79], v[140:143], v[232:235], v[76:79]
	v_mfma_f32_16x16x32_bf16 v[72:75], v[152:155], v[232:235], v[72:75]
	v_mfma_f32_16x16x32_bf16 v[124:127], v[148:151], v[190:193], v[124:127]
	v_mfma_f32_16x16x32_bf16 v[120:123], v[156:159], v[190:193], v[120:123]
	v_mfma_f32_16x16x32_bf16 v[108:111], v[148:151], v[198:201], v[108:111]
	v_mfma_f32_16x16x32_bf16 v[104:107], v[156:159], v[198:201], v[104:107]
	v_mfma_f32_16x16x32_bf16 v[92:95], v[148:151], v[228:231], v[92:95]
	v_mfma_f32_16x16x32_bf16 v[88:91], v[156:159], v[228:231], v[88:91]
	v_mfma_f32_16x16x32_bf16 v[76:79], v[148:151], v[236:239], v[76:79]
	v_mfma_f32_16x16x32_bf16 v[72:75], v[156:159], v[236:239], v[72:75]
	s_setprio 0
	s_setprio 1
	v_mfma_f32_16x16x32_bf16 v[116:119], v[170:173], v[186:189], v[116:119]
	v_mfma_f32_16x16x32_bf16 v[112:115], v[178:181], v[186:189], v[112:115]
	v_mfma_f32_16x16x32_bf16 v[100:103], v[170:173], v[194:197], v[100:103]
	v_mfma_f32_16x16x32_bf16 v[96:99], v[178:181], v[194:197], v[96:99]
	v_mfma_f32_16x16x32_bf16 v[84:87], v[170:173], v[202:205], v[84:87]
	v_mfma_f32_16x16x32_bf16 v[80:83], v[178:181], v[202:205], v[80:83]
	v_mfma_f32_16x16x32_bf16 v[68:71], v[170:173], v[232:235], v[68:71]
	v_mfma_f32_16x16x32_bf16 v[64:67], v[178:181], v[232:235], v[64:67]
	v_mfma_f32_16x16x32_bf16 v[116:119], v[174:177], v[190:193], v[116:119]
	v_mfma_f32_16x16x32_bf16 v[112:115], v[182:185], v[190:193], v[112:115]
	v_mfma_f32_16x16x32_bf16 v[100:103], v[174:177], v[198:201], v[100:103]
	v_mfma_f32_16x16x32_bf16 v[96:99], v[182:185], v[198:201], v[96:99]
	v_mfma_f32_16x16x32_bf16 v[84:87], v[174:177], v[228:231], v[84:87]
	v_mfma_f32_16x16x32_bf16 v[80:83], v[182:185], v[228:231], v[80:83]
	v_mfma_f32_16x16x32_bf16 v[68:71], v[174:177], v[236:239], v[68:71]
	v_mfma_f32_16x16x32_bf16 v[64:67], v[182:185], v[236:239], v[64:67]
	s_setprio 0
	s_barrier
	ds_read_b128 v[186:189], v146 offset:16384
	ds_read_b128 v[190:193], v146 offset:17408
	ds_read_b128 v[194:197], v146 offset:18432
	ds_read_b128 v[198:201], v146 offset:19456
	ds_read_b128 v[202:205], v146 offset:20480
	ds_read_b128 v[228:231], v146 offset:21504
	ds_read_b128 v[232:235], v146 offset:22528
	ds_read_b128 v[236:239], v146 offset:23552
	s_add_i32 s42, s42, s77
	s_mov_b32 m0, s42
	v_lshl_add_u64 v[166:167], s[16:17], 0, v[160:161]
	global_load_lds_dwordx4 v[166:167], off
	s_add_i32 m0, s42, 0x2000
	s_add_u32 s42, s16, 0x40000
	v_lshl_add_u64 v[168:169], s[16:17], 0, v[128:129]
	s_addc_u32 s43, s17, 0
	s_add_i32 s44, s44, s77
	global_load_lds_dwordx4 v[168:169], off
	v_lshl_add_u64 v[206:207], s[42:43], 0, v[160:161]
	s_mov_b32 m0, s44
	v_lshl_add_u64 v[240:241], s[18:19], 0, v[130:131]
	global_load_lds_dwordx4 v[206:207], off
	v_lshl_add_u64 v[206:207], s[42:43], 0, v[128:129]
	s_add_i32 m0, s44, 0x2000
	s_nop 0
	global_load_lds_dwordx4 v[206:207], off
	v_lshl_add_u64 v[206:207], s[18:19], 0, v[132:133]
	s_mov_b32 m0, s23
	s_nop 0
	global_load_lds_dwordx4 v[206:207], off
	s_mov_b32 m0, s24
	s_nop 0
	global_load_lds_dwordx4 v[240:241], off
	s_waitcnt vmcnt(8)
	s_waitcnt lgkmcnt(0)
	s_barrier
	s_setprio 1
	s_waitcnt lgkmcnt(0)
	v_mfma_f32_16x16x32_bf16 v[60:63], v[140:143], v[186:189], v[60:63]
	v_mfma_f32_16x16x32_bf16 v[56:59], v[152:155], v[186:189], v[56:59]
	v_mfma_f32_16x16x32_bf16 v[44:47], v[140:143], v[194:197], v[44:47]
	v_mfma_f32_16x16x32_bf16 v[40:43], v[152:155], v[194:197], v[40:43]
	v_mfma_f32_16x16x32_bf16 v[28:31], v[140:143], v[202:205], v[28:31]
	v_mfma_f32_16x16x32_bf16 v[24:27], v[152:155], v[202:205], v[24:27]
	v_mfma_f32_16x16x32_bf16 v[12:15], v[140:143], v[232:235], v[12:15]
	v_mfma_f32_16x16x32_bf16 v[8:11], v[152:155], v[232:235], v[8:11]
	v_mfma_f32_16x16x32_bf16 v[60:63], v[148:151], v[190:193], v[60:63]
	v_mfma_f32_16x16x32_bf16 v[56:59], v[156:159], v[190:193], v[56:59]
	v_mfma_f32_16x16x32_bf16 v[44:47], v[148:151], v[198:201], v[44:47]
	v_mfma_f32_16x16x32_bf16 v[40:43], v[156:159], v[198:201], v[40:43]
	v_mfma_f32_16x16x32_bf16 v[28:31], v[148:151], v[228:231], v[28:31]
	v_mfma_f32_16x16x32_bf16 v[24:27], v[156:159], v[228:231], v[24:27]
	v_mfma_f32_16x16x32_bf16 v[12:15], v[148:151], v[236:239], v[12:15]
	v_mfma_f32_16x16x32_bf16 v[8:11], v[156:159], v[236:239], v[8:11]
	s_setprio 0
	s_setprio 1
	v_mfma_f32_16x16x32_bf16 v[52:55], v[170:173], v[186:189], v[52:55]
	v_mfma_f32_16x16x32_bf16 v[48:51], v[178:181], v[186:189], v[48:51]
	v_mfma_f32_16x16x32_bf16 v[36:39], v[170:173], v[194:197], v[36:39]
	v_mfma_f32_16x16x32_bf16 v[32:35], v[178:181], v[194:197], v[32:35]
	v_mfma_f32_16x16x32_bf16 v[20:23], v[170:173], v[202:205], v[20:23]
	v_mfma_f32_16x16x32_bf16 v[16:19], v[178:181], v[202:205], v[16:19]
	v_mfma_f32_16x16x32_bf16 v[4:7], v[170:173], v[232:235], v[4:7]
	v_mfma_f32_16x16x32_bf16 v[0:3], v[178:181], v[232:235], v[0:3]
	v_mfma_f32_16x16x32_bf16 v[52:55], v[174:177], v[190:193], v[52:55]
	v_mfma_f32_16x16x32_bf16 v[48:51], v[182:185], v[190:193], v[48:51]
	v_mfma_f32_16x16x32_bf16 v[36:39], v[174:177], v[198:201], v[36:39]
	v_mfma_f32_16x16x32_bf16 v[32:35], v[182:185], v[198:201], v[32:35]
	v_mfma_f32_16x16x32_bf16 v[20:23], v[174:177], v[228:231], v[20:23]
	v_mfma_f32_16x16x32_bf16 v[16:19], v[182:185], v[228:231], v[16:19]
	v_mfma_f32_16x16x32_bf16 v[4:7], v[174:177], v[236:239], v[4:7]
	v_mfma_f32_16x16x32_bf16 v[0:3], v[182:185], v[236:239], v[0:3]
	s_setprio 0
	s_barrier
	s_add_i32 s42, 0, 0x18000
	v_add_u32_e32 v147, s42, v145
	s_add_i32 s43, 0, 0x1c000
	ds_read_b128 v[140:143], v147
	ds_read_b128 v[148:151], v147 offset:1024
	ds_read_b128 v[152:155], v147 offset:2048
	ds_read_b128 v[156:159], v147 offset:3072
	v_add_u32_e32 v147, s43, v145
	ds_read_b128 v[170:173], v147
	ds_read_b128 v[174:177], v147 offset:1024
	ds_read_b128 v[178:181], v147 offset:2048
	ds_read_b128 v[182:185], v147 offset:3072
	s_add_u32 s18, s18, 0x40000
	s_addc_u32 s19, s19, 0
	s_mov_b32 m0, s25
	v_lshl_add_u64 v[242:243], s[18:19], 0, v[132:133]
	ds_read_b128 v[186:189], v146 offset:32768
	ds_read_b128 v[190:193], v146 offset:33792
	ds_read_b128 v[194:197], v146 offset:34816
	ds_read_b128 v[198:201], v146 offset:35840
	ds_read_b128 v[202:205], v146 offset:36864
	ds_read_b128 v[228:231], v146 offset:37888
	ds_read_b128 v[232:235], v146 offset:38912
	ds_read_b128 v[236:239], v146 offset:39936
	global_load_lds_dwordx4 v[242:243], off
	v_lshl_add_u64 v[242:243], s[18:19], 0, v[130:131]
	s_mov_b32 m0, s26
	s_nop 0
	global_load_lds_dwordx4 v[242:243], off
	s_waitcnt vmcnt(8)
	s_waitcnt lgkmcnt(0)
	s_barrier
	s_setprio 1
	s_waitcnt lgkmcnt(0)
	v_mfma_f32_16x16x32_bf16 v[124:127], v[140:143], v[186:189], v[124:127]
	v_mfma_f32_16x16x32_bf16 v[120:123], v[152:155], v[186:189], v[120:123]
	v_mfma_f32_16x16x32_bf16 v[108:111], v[140:143], v[194:197], v[108:111]
	v_mfma_f32_16x16x32_bf16 v[104:107], v[152:155], v[194:197], v[104:107]
	v_mfma_f32_16x16x32_bf16 v[92:95], v[140:143], v[202:205], v[92:95]
	v_mfma_f32_16x16x32_bf16 v[88:91], v[152:155], v[202:205], v[88:91]
	v_mfma_f32_16x16x32_bf16 v[76:79], v[140:143], v[232:235], v[76:79]
	v_mfma_f32_16x16x32_bf16 v[72:75], v[152:155], v[232:235], v[72:75]
	v_mfma_f32_16x16x32_bf16 v[124:127], v[148:151], v[190:193], v[124:127]
	v_mfma_f32_16x16x32_bf16 v[120:123], v[156:159], v[190:193], v[120:123]
	v_mfma_f32_16x16x32_bf16 v[108:111], v[148:151], v[198:201], v[108:111]
	v_mfma_f32_16x16x32_bf16 v[104:107], v[156:159], v[198:201], v[104:107]
	v_mfma_f32_16x16x32_bf16 v[92:95], v[148:151], v[228:231], v[92:95]
	v_mfma_f32_16x16x32_bf16 v[88:91], v[156:159], v[228:231], v[88:91]
	v_mfma_f32_16x16x32_bf16 v[76:79], v[148:151], v[236:239], v[76:79]
	v_mfma_f32_16x16x32_bf16 v[72:75], v[156:159], v[236:239], v[72:75]
	s_setprio 0
	s_setprio 1
	v_mfma_f32_16x16x32_bf16 v[116:119], v[170:173], v[186:189], v[116:119]
	v_mfma_f32_16x16x32_bf16 v[112:115], v[178:181], v[186:189], v[112:115]
	v_mfma_f32_16x16x32_bf16 v[100:103], v[170:173], v[194:197], v[100:103]
	v_mfma_f32_16x16x32_bf16 v[96:99], v[178:181], v[194:197], v[96:99]
	v_mfma_f32_16x16x32_bf16 v[84:87], v[170:173], v[202:205], v[84:87]
	v_mfma_f32_16x16x32_bf16 v[80:83], v[178:181], v[202:205], v[80:83]
	v_mfma_f32_16x16x32_bf16 v[68:71], v[170:173], v[232:235], v[68:71]
	v_mfma_f32_16x16x32_bf16 v[64:67], v[178:181], v[232:235], v[64:67]
	v_mfma_f32_16x16x32_bf16 v[116:119], v[174:177], v[190:193], v[116:119]
	v_mfma_f32_16x16x32_bf16 v[112:115], v[182:185], v[190:193], v[112:115]
	v_mfma_f32_16x16x32_bf16 v[100:103], v[174:177], v[198:201], v[100:103]
	v_mfma_f32_16x16x32_bf16 v[96:99], v[182:185], v[198:201], v[96:99]
	v_mfma_f32_16x16x32_bf16 v[84:87], v[174:177], v[228:231], v[84:87]
	v_mfma_f32_16x16x32_bf16 v[80:83], v[182:185], v[228:231], v[80:83]
	v_mfma_f32_16x16x32_bf16 v[68:71], v[174:177], v[236:239], v[68:71]
	v_mfma_f32_16x16x32_bf16 v[64:67], v[182:185], v[236:239], v[64:67]
	s_setprio 0
	s_barrier
	ds_read_b128 v[186:189], v146 offset:49152
	ds_read_b128 v[190:193], v146 offset:50176
	ds_read_b128 v[194:197], v146 offset:51200
	ds_read_b128 v[198:201], v146 offset:52224
	ds_read_b128 v[202:205], v146 offset:53248
	ds_read_b128 v[228:231], v146 offset:54272
	ds_read_b128 v[232:235], v146 offset:55296
	ds_read_b128 v[236:239], v146 offset:56320
	s_add_i32 s18, s42, s77
	s_mov_b32 m0, s18
	v_lshl_add_u64 v[166:167], v[166:167], 0, s[96:97]
	global_load_lds_dwordx4 v[166:167], off
	s_add_i32 m0, s18, 0x2000
	s_add_u32 s16, s16, 0x40080
	v_lshl_add_u64 v[166:167], v[168:169], 0, s[96:97]
	s_addc_u32 s17, s17, 0
	s_add_i32 s18, s43, s77
	global_load_lds_dwordx4 v[166:167], off
	v_lshl_add_u64 v[166:167], s[16:17], 0, v[160:161]
	s_mov_b32 m0, s18
	s_nop 0
	global_load_lds_dwordx4 v[166:167], off
	v_lshl_add_u64 v[166:167], s[16:17], 0, v[128:129]
	s_add_i32 m0, s18, 0x2000
	s_nop 0
	global_load_lds_dwordx4 v[166:167], off
	v_lshl_add_u64 v[166:167], v[206:207], 0, s[96:97]
	s_mov_b32 m0, s31
	s_nop 0
	global_load_lds_dwordx4 v[166:167], off
	v_lshl_add_u64 v[166:167], v[240:241], 0, s[96:97]
	s_mov_b32 m0, s34
	s_nop 0
	global_load_lds_dwordx4 v[166:167], off
	s_waitcnt vmcnt(8)
	s_waitcnt lgkmcnt(0)
	s_barrier
	s_setprio 1
	s_waitcnt lgkmcnt(0)
	v_mfma_f32_16x16x32_bf16 v[60:63], v[140:143], v[186:189], v[60:63]
	v_mfma_f32_16x16x32_bf16 v[56:59], v[152:155], v[186:189], v[56:59]
	v_mfma_f32_16x16x32_bf16 v[44:47], v[140:143], v[194:197], v[44:47]
	v_mfma_f32_16x16x32_bf16 v[40:43], v[152:155], v[194:197], v[40:43]
	v_mfma_f32_16x16x32_bf16 v[28:31], v[140:143], v[202:205], v[28:31]
	v_mfma_f32_16x16x32_bf16 v[24:27], v[152:155], v[202:205], v[24:27]
	v_mfma_f32_16x16x32_bf16 v[12:15], v[140:143], v[232:235], v[12:15]
	v_mfma_f32_16x16x32_bf16 v[8:11], v[152:155], v[232:235], v[8:11]
	v_mfma_f32_16x16x32_bf16 v[60:63], v[148:151], v[190:193], v[60:63]
	v_mfma_f32_16x16x32_bf16 v[56:59], v[156:159], v[190:193], v[56:59]
	v_mfma_f32_16x16x32_bf16 v[44:47], v[148:151], v[198:201], v[44:47]
	v_mfma_f32_16x16x32_bf16 v[40:43], v[156:159], v[198:201], v[40:43]
	v_mfma_f32_16x16x32_bf16 v[28:31], v[148:151], v[228:231], v[28:31]
	v_mfma_f32_16x16x32_bf16 v[24:27], v[156:159], v[228:231], v[24:27]
	v_mfma_f32_16x16x32_bf16 v[12:15], v[148:151], v[236:239], v[12:15]
	v_mfma_f32_16x16x32_bf16 v[8:11], v[156:159], v[236:239], v[8:11]
	s_setprio 0
	s_setprio 1
	v_mfma_f32_16x16x32_bf16 v[52:55], v[170:173], v[186:189], v[52:55]
	v_mfma_f32_16x16x32_bf16 v[48:51], v[178:181], v[186:189], v[48:51]
	v_mfma_f32_16x16x32_bf16 v[36:39], v[170:173], v[194:197], v[36:39]
	v_mfma_f32_16x16x32_bf16 v[32:35], v[178:181], v[194:197], v[32:35]
	v_mfma_f32_16x16x32_bf16 v[20:23], v[170:173], v[202:205], v[20:23]
	v_mfma_f32_16x16x32_bf16 v[16:19], v[178:181], v[202:205], v[16:19]
	v_mfma_f32_16x16x32_bf16 v[4:7], v[170:173], v[232:235], v[4:7]
	v_mfma_f32_16x16x32_bf16 v[0:3], v[178:181], v[232:235], v[0:3]
	v_mfma_f32_16x16x32_bf16 v[52:55], v[174:177], v[190:193], v[52:55]
	v_mfma_f32_16x16x32_bf16 v[48:51], v[182:185], v[190:193], v[48:51]
	v_mfma_f32_16x16x32_bf16 v[36:39], v[174:177], v[198:201], v[36:39]
	v_mfma_f32_16x16x32_bf16 v[32:35], v[182:185], v[198:201], v[32:35]
	v_mfma_f32_16x16x32_bf16 v[20:23], v[174:177], v[228:231], v[20:23]
	v_mfma_f32_16x16x32_bf16 v[16:19], v[182:185], v[228:231], v[16:19]
	v_mfma_f32_16x16x32_bf16 v[4:7], v[174:177], v[236:239], v[4:7]
	v_mfma_f32_16x16x32_bf16 v[0:3], v[182:185], v[236:239], v[0:3]
	s_setprio 0
	s_add_i32 s41, s41, 2
	s_add_u32 s39, s39, 0x100
	s_addc_u32 s40, s40, 0
	s_add_u32 s14, s14, 0x100
	s_addc_u32 s15, s15, 0
	s_cmp_gt_u32 s41, 13
	s_barrier
	s_cbranch_scc0 .LBB0_290
	v_readlane_b32 s14, v253, 23
	v_readlane_b32 s15, v253, 24
	s_and_b64 vcc, exec, s[14:15]
	s_cbranch_vccz .LBB0_293
	s_barrier

.LBB0_483:
	s_add_i32 s39, 0, 0x10000
	s_add_i32 s42, 0, 0x14000
	v_add_u32_e32 v140, s39, v229
	v_add_u32_e32 v156, s42, v229
	ds_read_b128 v[128:131], v140
	ds_read_b128 v[132:135], v140 offset:1024
	ds_read_b128 v[136:139], v140 offset:2048
	ds_read_b128 v[140:143], v140 offset:3072
	ds_read_b128 v[144:147], v156
	ds_read_b128 v[148:151], v156 offset:1024
	ds_read_b128 v[152:155], v156 offset:2048
	ds_read_b128 v[156:159], v156 offset:3072
	v_lshl_add_u64 v[206:207], s[8:9], 0, v[188:189]
	s_add_i32 m0, s22, 0xc000
	ds_read_b128 v[190:193], v230
	ds_read_b128 v[194:197], v230 offset:1024
	ds_read_b128 v[198:201], v230 offset:2048
	ds_read_b128 v[202:205], v230 offset:3072
	ds_read_b128 v[232:235], v230 offset:4096
	ds_read_b128 v[236:239], v230 offset:5120
	ds_read_b128 v[240:243], v230 offset:6144
	ds_read_b128 v[244:247], v230 offset:7168
	s_add_u32 s16, s8, 0xfffc0080
	s_addc_u32 s17, s9, -1
	s_cmp_eq_u32 s38, 12
	s_cselect_b32 s19, s11, s17
	s_cselect_b32 s18, s34, s16
	s_cselect_b32 s17, s1, s37
	s_cselect_b32 s16, s35, s36
	global_load_lds_dwordx4 v[206:207], off
	v_lshl_add_u64 v[206:207], s[8:9], 0, v[186:187]
	s_add_i32 m0, s22, 0xe000
	s_nop 0
	global_load_lds_dwordx4 v[206:207], off
	s_waitcnt vmcnt(8)
	s_waitcnt lgkmcnt(0)
	s_barrier
	s_setprio 1
	s_waitcnt lgkmcnt(0)
	v_mfma_f32_16x16x32_bf16 v[124:127], v[128:131], v[190:193], v[124:127]
	v_mfma_f32_16x16x32_bf16 v[120:123], v[136:139], v[190:193], v[120:123]
	v_mfma_f32_16x16x32_bf16 v[108:111], v[128:131], v[198:201], v[108:111]
	v_mfma_f32_16x16x32_bf16 v[104:107], v[136:139], v[198:201], v[104:107]
	v_mfma_f32_16x16x32_bf16 v[92:95], v[128:131], v[232:235], v[92:95]
	v_mfma_f32_16x16x32_bf16 v[88:91], v[136:139], v[232:235], v[88:91]
	v_mfma_f32_16x16x32_bf16 v[76:79], v[128:131], v[240:243], v[76:79]
	v_mfma_f32_16x16x32_bf16 v[72:75], v[136:139], v[240:243], v[72:75]
	v_mfma_f32_16x16x32_bf16 v[124:127], v[132:135], v[194:197], v[124:127]
	v_mfma_f32_16x16x32_bf16 v[120:123], v[140:143], v[194:197], v[120:123]
	v_mfma_f32_16x16x32_bf16 v[108:111], v[132:135], v[202:205], v[108:111]
	v_mfma_f32_16x16x32_bf16 v[104:107], v[140:143], v[202:205], v[104:107]
	v_mfma_f32_16x16x32_bf16 v[92:95], v[132:135], v[236:239], v[92:95]
	v_mfma_f32_16x16x32_bf16 v[88:91], v[140:143], v[236:239], v[88:91]
	v_mfma_f32_16x16x32_bf16 v[76:79], v[132:135], v[244:247], v[76:79]
	v_mfma_f32_16x16x32_bf16 v[72:75], v[140:143], v[244:247], v[72:75]
	s_setprio 0
	s_setprio 1
	v_mfma_f32_16x16x32_bf16 v[116:119], v[144:147], v[190:193], v[116:119]
	v_mfma_f32_16x16x32_bf16 v[112:115], v[152:155], v[190:193], v[112:115]
	v_mfma_f32_16x16x32_bf16 v[100:103], v[144:147], v[198:201], v[100:103]
	v_mfma_f32_16x16x32_bf16 v[96:99], v[152:155], v[198:201], v[96:99]
	v_mfma_f32_16x16x32_bf16 v[84:87], v[144:147], v[232:235], v[84:87]
	v_mfma_f32_16x16x32_bf16 v[80:83], v[152:155], v[232:235], v[80:83]
	v_mfma_f32_16x16x32_bf16 v[68:71], v[144:147], v[240:243], v[68:71]
	v_mfma_f32_16x16x32_bf16 v[64:67], v[152:155], v[240:243], v[64:67]
	v_mfma_f32_16x16x32_bf16 v[116:119], v[148:151], v[194:197], v[116:119]
	v_mfma_f32_16x16x32_bf16 v[112:115], v[156:159], v[194:197], v[112:115]
	v_mfma_f32_16x16x32_bf16 v[100:103], v[148:151], v[202:205], v[100:103]
	v_mfma_f32_16x16x32_bf16 v[96:99], v[156:159], v[202:205], v[96:99]
	v_mfma_f32_16x16x32_bf16 v[84:87], v[148:151], v[236:239], v[84:87]
	v_mfma_f32_16x16x32_bf16 v[80:83], v[156:159], v[236:239], v[80:83]
	v_mfma_f32_16x16x32_bf16 v[68:71], v[148:151], v[244:247], v[68:71]
	v_mfma_f32_16x16x32_bf16 v[64:67], v[156:159], v[244:247], v[64:67]
	s_setprio 0
	s_barrier
	ds_read_b128 v[190:193], v230 offset:16384
	ds_read_b128 v[194:197], v230 offset:17408
	ds_read_b128 v[198:201], v230 offset:18432
	ds_read_b128 v[202:205], v230 offset:19456
	ds_read_b128 v[232:235], v230 offset:20480
	ds_read_b128 v[236:239], v230 offset:21504
	ds_read_b128 v[240:243], v230 offset:22528
	ds_read_b128 v[244:247], v230 offset:23552
	s_add_i32 s39, s39, s77
	s_mov_b32 m0, s39
	v_lshl_add_u64 v[206:207], s[16:17], 0, v[174:175]
	global_load_lds_dwordx4 v[206:207], off
	s_add_i32 m0, s39, 0x2000
	s_add_u32 s40, s16, 0x40000
	v_lshl_add_u64 v[248:249], s[16:17], 0, v[170:171]
	s_addc_u32 s41, s17, 0
	s_add_i32 s39, s42, s77
	global_load_lds_dwordx4 v[248:249], off
	v_lshl_add_u64 v[250:251], s[40:41], 0, v[174:175]
	s_mov_b32 m0, s39
	v_lshl_add_u64 v[166:167], s[18:19], 0, v[172:173]
	global_load_lds_dwordx4 v[250:251], off
	v_lshl_add_u64 v[250:251], s[40:41], 0, v[170:171]
	s_add_i32 m0, s39, 0x2000
	s_nop 0
	global_load_lds_dwordx4 v[250:251], off
	v_lshl_add_u64 v[250:251], s[18:19], 0, v[176:177]
	s_mov_b32 m0, s22
	s_nop 0
	global_load_lds_dwordx4 v[250:251], off
	s_mov_b32 m0, s23
	s_nop 0
	global_load_lds_dwordx4 v[166:167], off
	s_waitcnt vmcnt(8)
	s_waitcnt lgkmcnt(0)
	s_barrier
	s_setprio 1
	s_waitcnt lgkmcnt(0)
	v_mfma_f32_16x16x32_bf16 v[60:63], v[128:131], v[190:193], v[60:63]
	v_mfma_f32_16x16x32_bf16 v[56:59], v[136:139], v[190:193], v[56:59]
	v_mfma_f32_16x16x32_bf16 v[44:47], v[128:131], v[198:201], v[44:47]
	v_mfma_f32_16x16x32_bf16 v[40:43], v[136:139], v[198:201], v[40:43]
	v_mfma_f32_16x16x32_bf16 v[28:31], v[128:131], v[232:235], v[28:31]
	v_mfma_f32_16x16x32_bf16 v[24:27], v[136:139], v[232:235], v[24:27]
	v_mfma_f32_16x16x32_bf16 v[12:15], v[128:131], v[240:243], v[12:15]
	v_mfma_f32_16x16x32_bf16 v[8:11], v[136:139], v[240:243], v[8:11]
	v_mfma_f32_16x16x32_bf16 v[60:63], v[132:135], v[194:197], v[60:63]
	v_mfma_f32_16x16x32_bf16 v[56:59], v[140:143], v[194:197], v[56:59]
	v_mfma_f32_16x16x32_bf16 v[44:47], v[132:135], v[202:205], v[44:47]
	v_mfma_f32_16x16x32_bf16 v[40:43], v[140:143], v[202:205], v[40:43]
	v_mfma_f32_16x16x32_bf16 v[28:31], v[132:135], v[236:239], v[28:31]
	v_mfma_f32_16x16x32_bf16 v[24:27], v[140:143], v[236:239], v[24:27]
	v_mfma_f32_16x16x32_bf16 v[12:15], v[132:135], v[244:247], v[12:15]
	v_mfma_f32_16x16x32_bf16 v[8:11], v[140:143], v[244:247], v[8:11]
	s_setprio 0
	s_setprio 1
	v_mfma_f32_16x16x32_bf16 v[52:55], v[144:147], v[190:193], v[52:55]
	v_mfma_f32_16x16x32_bf16 v[48:51], v[152:155], v[190:193], v[48:51]
	v_mfma_f32_16x16x32_bf16 v[36:39], v[144:147], v[198:201], v[36:39]
	v_mfma_f32_16x16x32_bf16 v[32:35], v[152:155], v[198:201], v[32:35]
	v_mfma_f32_16x16x32_bf16 v[20:23], v[144:147], v[232:235], v[20:23]
	v_mfma_f32_16x16x32_bf16 v[16:19], v[152:155], v[232:235], v[16:19]
	v_mfma_f32_16x16x32_bf16 v[4:7], v[144:147], v[240:243], v[4:7]
	v_mfma_f32_16x16x32_bf16 v[0:3], v[152:155], v[240:243], v[0:3]
	v_mfma_f32_16x16x32_bf16 v[52:55], v[148:151], v[194:197], v[52:55]
	v_mfma_f32_16x16x32_bf16 v[48:51], v[156:159], v[194:197], v[48:51]
	v_mfma_f32_16x16x32_bf16 v[36:39], v[148:151], v[202:205], v[36:39]
	v_mfma_f32_16x16x32_bf16 v[32:35], v[156:159], v[202:205], v[32:35]
	v_mfma_f32_16x16x32_bf16 v[20:23], v[148:151], v[236:239], v[20:23]
	v_mfma_f32_16x16x32_bf16 v[16:19], v[156:159], v[236:239], v[16:19]
	v_mfma_f32_16x16x32_bf16 v[4:7], v[148:151], v[244:247], v[4:7]
	v_mfma_f32_16x16x32_bf16 v[0:3], v[156:159], v[244:247], v[0:3]
	s_setprio 0
	s_barrier
	s_add_i32 s39, 0, 0x18000
	s_add_i32 s40, 0, 0x1c000
	v_add_u32_e32 v140, s39, v229
	v_add_u32_e32 v156, s40, v229
	ds_read_b128 v[128:131], v140
	ds_read_b128 v[132:135], v140 offset:1024
	ds_read_b128 v[136:139], v140 offset:2048
	ds_read_b128 v[140:143], v140 offset:3072
	ds_read_b128 v[144:147], v156
	ds_read_b128 v[148:151], v156 offset:1024
	ds_read_b128 v[152:155], v156 offset:2048
	ds_read_b128 v[156:159], v156 offset:3072
	s_add_u32 s18, s18, 0x40000
	s_addc_u32 s19, s19, 0
	s_mov_b32 m0, s24
	v_lshl_add_u64 v[168:169], s[18:19], 0, v[176:177]
	ds_read_b128 v[190:193], v230 offset:32768
	ds_read_b128 v[194:197], v230 offset:33792
	ds_read_b128 v[198:201], v230 offset:34816
	ds_read_b128 v[202:205], v230 offset:35840
	ds_read_b128 v[232:235], v230 offset:36864
	ds_read_b128 v[236:239], v230 offset:37888
	ds_read_b128 v[240:243], v230 offset:38912
	ds_read_b128 v[244:247], v230 offset:39936
	global_load_lds_dwordx4 v[168:169], off
	v_lshl_add_u64 v[168:169], s[18:19], 0, v[172:173]
	s_mov_b32 m0, s25
	s_nop 0
	global_load_lds_dwordx4 v[168:169], off
	s_waitcnt vmcnt(8)
	s_waitcnt lgkmcnt(0)
	s_barrier
	s_setprio 1
	s_waitcnt lgkmcnt(0)
	v_mfma_f32_16x16x32_bf16 v[124:127], v[128:131], v[190:193], v[124:127]
	v_mfma_f32_16x16x32_bf16 v[120:123], v[136:139], v[190:193], v[120:123]
	v_mfma_f32_16x16x32_bf16 v[108:111], v[128:131], v[198:201], v[108:111]
	v_mfma_f32_16x16x32_bf16 v[104:107], v[136:139], v[198:201], v[104:107]
	v_mfma_f32_16x16x32_bf16 v[92:95], v[128:131], v[232:235], v[92:95]
	v_mfma_f32_16x16x32_bf16 v[88:91], v[136:139], v[232:235], v[88:91]
	v_mfma_f32_16x16x32_bf16 v[76:79], v[128:131], v[240:243], v[76:79]
	v_mfma_f32_16x16x32_bf16 v[72:75], v[136:139], v[240:243], v[72:75]
	v_mfma_f32_16x16x32_bf16 v[124:127], v[132:135], v[194:197], v[124:127]
	v_mfma_f32_16x16x32_bf16 v[120:123], v[140:143], v[194:197], v[120:123]
	v_mfma_f32_16x16x32_bf16 v[108:111], v[132:135], v[202:205], v[108:111]
	v_mfma_f32_16x16x32_bf16 v[104:107], v[140:143], v[202:205], v[104:107]
	v_mfma_f32_16x16x32_bf16 v[92:95], v[132:135], v[236:239], v[92:95]
	v_mfma_f32_16x16x32_bf16 v[88:91], v[140:143], v[236:239], v[88:91]
	v_mfma_f32_16x16x32_bf16 v[76:79], v[132:135], v[244:247], v[76:79]
	v_mfma_f32_16x16x32_bf16 v[72:75], v[140:143], v[244:247], v[72:75]
	s_setprio 0
	s_setprio 1
	v_mfma_f32_16x16x32_bf16 v[116:119], v[144:147], v[190:193], v[116:119]
	v_mfma_f32_16x16x32_bf16 v[112:115], v[152:155], v[190:193], v[112:115]
	v_mfma_f32_16x16x32_bf16 v[100:103], v[144:147], v[198:201], v[100:103]
	v_mfma_f32_16x16x32_bf16 v[96:99], v[152:155], v[198:201], v[96:99]
	v_mfma_f32_16x16x32_bf16 v[84:87], v[144:147], v[232:235], v[84:87]
	v_mfma_f32_16x16x32_bf16 v[80:83], v[152:155], v[232:235], v[80:83]
	v_mfma_f32_16x16x32_bf16 v[68:71], v[144:147], v[240:243], v[68:71]
	v_mfma_f32_16x16x32_bf16 v[64:67], v[152:155], v[240:243], v[64:67]
	v_mfma_f32_16x16x32_bf16 v[116:119], v[148:151], v[194:197], v[116:119]
	v_mfma_f32_16x16x32_bf16 v[112:115], v[156:159], v[194:197], v[112:115]
	v_mfma_f32_16x16x32_bf16 v[100:103], v[148:151], v[202:205], v[100:103]
	v_mfma_f32_16x16x32_bf16 v[96:99], v[156:159], v[202:205], v[96:99]
	v_mfma_f32_16x16x32_bf16 v[84:87], v[148:151], v[236:239], v[84:87]
	v_mfma_f32_16x16x32_bf16 v[80:83], v[156:159], v[236:239], v[80:83]
	v_mfma_f32_16x16x32_bf16 v[68:71], v[148:151], v[244:247], v[68:71]
	v_mfma_f32_16x16x32_bf16 v[64:67], v[156:159], v[244:247], v[64:67]
	s_setprio 0
	s_barrier
	ds_read_b128 v[190:193], v230 offset:49152
	ds_read_b128 v[194:197], v230 offset:50176
	ds_read_b128 v[198:201], v230 offset:51200
	ds_read_b128 v[202:205], v230 offset:52224
	ds_read_b128 v[232:235], v230 offset:53248
	ds_read_b128 v[236:239], v230 offset:54272
	ds_read_b128 v[240:243], v230 offset:55296
	ds_read_b128 v[244:247], v230 offset:56320
	s_add_i32 s18, s39, s77
	s_mov_b32 m0, s18
	v_lshl_add_u64 v[168:169], v[206:207], 0, s[96:97]
	global_load_lds_dwordx4 v[168:169], off
	s_add_i32 m0, s18, 0x2000
	s_add_u32 s16, s16, 0x40080
	v_lshl_add_u64 v[168:169], v[248:249], 0, s[96:97]
	s_addc_u32 s17, s17, 0
	s_add_i32 s18, s40, s77
	global_load_lds_dwordx4 v[168:169], off
	v_lshl_add_u64 v[168:169], s[16:17], 0, v[174:175]
	s_mov_b32 m0, s18
	v_lshl_add_u64 v[166:167], v[166:167], 0, s[96:97]
	global_load_lds_dwordx4 v[168:169], off
	v_lshl_add_u64 v[168:169], s[16:17], 0, v[170:171]
	s_add_i32 m0, s18, 0x2000
	s_nop 0
	global_load_lds_dwordx4 v[168:169], off
	v_lshl_add_u64 v[168:169], v[250:251], 0, s[96:97]
	s_mov_b32 m0, s28
	s_nop 0
	global_load_lds_dwordx4 v[168:169], off
	s_mov_b32 m0, s29
	s_nop 0
	global_load_lds_dwordx4 v[166:167], off
	s_waitcnt vmcnt(8)
	s_waitcnt lgkmcnt(0)
	s_barrier
	s_setprio 1
	s_waitcnt lgkmcnt(0)
	v_mfma_f32_16x16x32_bf16 v[60:63], v[128:131], v[190:193], v[60:63]
	v_mfma_f32_16x16x32_bf16 v[56:59], v[136:139], v[190:193], v[56:59]
	v_mfma_f32_16x16x32_bf16 v[44:47], v[128:131], v[198:201], v[44:47]
	v_mfma_f32_16x16x32_bf16 v[40:43], v[136:139], v[198:201], v[40:43]
	v_mfma_f32_16x16x32_bf16 v[28:31], v[128:131], v[232:235], v[28:31]
	v_mfma_f32_16x16x32_bf16 v[24:27], v[136:139], v[232:235], v[24:27]
	v_mfma_f32_16x16x32_bf16 v[12:15], v[128:131], v[240:243], v[12:15]
	v_mfma_f32_16x16x32_bf16 v[8:11], v[136:139], v[240:243], v[8:11]
	v_mfma_f32_16x16x32_bf16 v[60:63], v[132:135], v[194:197], v[60:63]
	v_mfma_f32_16x16x32_bf16 v[56:59], v[140:143], v[194:197], v[56:59]
	v_mfma_f32_16x16x32_bf16 v[44:47], v[132:135], v[202:205], v[44:47]
	v_mfma_f32_16x16x32_bf16 v[40:43], v[140:143], v[202:205], v[40:43]
	v_mfma_f32_16x16x32_bf16 v[28:31], v[132:135], v[236:239], v[28:31]
	v_mfma_f32_16x16x32_bf16 v[24:27], v[140:143], v[236:239], v[24:27]
	v_mfma_f32_16x16x32_bf16 v[12:15], v[132:135], v[244:247], v[12:15]
	v_mfma_f32_16x16x32_bf16 v[8:11], v[140:143], v[244:247], v[8:11]
	s_setprio 0
	s_setprio 1
	v_mfma_f32_16x16x32_bf16 v[52:55], v[144:147], v[190:193], v[52:55]
	v_mfma_f32_16x16x32_bf16 v[48:51], v[152:155], v[190:193], v[48:51]
	v_mfma_f32_16x16x32_bf16 v[36:39], v[144:147], v[198:201], v[36:39]
	v_mfma_f32_16x16x32_bf16 v[32:35], v[152:155], v[198:201], v[32:35]
	v_mfma_f32_16x16x32_bf16 v[20:23], v[144:147], v[232:235], v[20:23]
	v_mfma_f32_16x16x32_bf16 v[16:19], v[152:155], v[232:235], v[16:19]
	v_mfma_f32_16x16x32_bf16 v[4:7], v[144:147], v[240:243], v[4:7]
	v_mfma_f32_16x16x32_bf16 v[0:3], v[152:155], v[240:243], v[0:3]
	v_mfma_f32_16x16x32_bf16 v[52:55], v[148:151], v[194:197], v[52:55]
	v_mfma_f32_16x16x32_bf16 v[48:51], v[156:159], v[194:197], v[48:51]
	v_mfma_f32_16x16x32_bf16 v[36:39], v[148:151], v[202:205], v[36:39]
	v_mfma_f32_16x16x32_bf16 v[32:35], v[156:159], v[202:205], v[32:35]
	v_mfma_f32_16x16x32_bf16 v[20:23], v[148:151], v[236:239], v[20:23]
	v_mfma_f32_16x16x32_bf16 v[16:19], v[156:159], v[236:239], v[16:19]
	v_mfma_f32_16x16x32_bf16 v[4:7], v[148:151], v[244:247], v[4:7]
	v_mfma_f32_16x16x32_bf16 v[0:3], v[156:159], v[244:247], v[0:3]
	s_setprio 0
	s_add_i32 s38, s38, 2
	s_add_u32 s36, s36, 0x100
	s_addc_u32 s37, s37, 0
	s_add_u32 s8, s8, 0x100
	s_addc_u32 s9, s9, 0
	s_cmp_gt_u32 s38, 13
	s_barrier
	s_cbranch_scc0 .LBB0_483
	v_readlane_b32 s8, v253, 23
	v_readlane_b32 s9, v253, 24
	s_and_b64 vcc, exec, s[8:9]
	s_cbranch_vccz .LBB0_486
	s_barrier

.LBB0_554:
	s_add_i32 s45, 0, 0x10000
	s_add_i32 s48, 0, 0x14000
	v_add_u32_e32 v150, s45, v157
	v_add_u32_e32 v154, s48, v157
	ds_read_b128 v[128:131], v150
	ds_read_b128 v[132:135], v150 offset:1024
	ds_read_b128 v[146:149], v150 offset:2048
	ds_read_b128 v[150:153], v150 offset:3072
	ds_read_b128 v[170:173], v154
	ds_read_b128 v[174:177], v154 offset:1024
	ds_read_b128 v[178:181], v154 offset:2048
	ds_read_b128 v[182:185], v154 offset:3072
	v_lshl_add_u64 v[154:155], s[18:19], 0, v[144:145]
	s_add_i32 m0, s27, 0xc000
	ds_read_b128 v[186:189], v159
	ds_read_b128 v[190:193], v159 offset:1024
	ds_read_b128 v[194:197], v159 offset:2048
	ds_read_b128 v[198:201], v159 offset:3072
	ds_read_b128 v[202:205], v159 offset:4096
	ds_read_b128 v[228:231], v159 offset:5120
	ds_read_b128 v[232:235], v159 offset:6144
	ds_read_b128 v[236:239], v159 offset:7168
	s_add_u32 s20, s18, 0xfff00080
	s_addc_u32 s21, s19, -1
	s_cmp_eq_u32 s44, 60
	s_cselect_b32 s23, s13, s21
	s_cselect_b32 s22, s40, s20
	s_cselect_b32 s21, s11, s43
	s_cselect_b32 s20, s41, s42
	global_load_lds_dwordx4 v[154:155], off
	v_lshl_add_u64 v[154:155], s[18:19], 0, v[142:143]
	s_add_i32 m0, s27, 0xe000
	s_nop 0
	global_load_lds_dwordx4 v[154:155], off
	s_waitcnt vmcnt(8)
	s_waitcnt lgkmcnt(0)
	s_barrier
	s_setprio 1
	s_waitcnt lgkmcnt(0)
	v_mfma_f32_16x16x32_bf16 v[124:127], v[128:131], v[186:189], v[124:127]
	v_mfma_f32_16x16x32_bf16 v[120:123], v[146:149], v[186:189], v[120:123]
	v_mfma_f32_16x16x32_bf16 v[116:119], v[128:131], v[194:197], v[116:119]
	v_mfma_f32_16x16x32_bf16 v[112:115], v[146:149], v[194:197], v[112:115]
	v_mfma_f32_16x16x32_bf16 v[108:111], v[128:131], v[202:205], v[108:111]
	v_mfma_f32_16x16x32_bf16 v[104:107], v[146:149], v[202:205], v[104:107]
	v_mfma_f32_16x16x32_bf16 v[100:103], v[128:131], v[232:235], v[100:103]
	v_mfma_f32_16x16x32_bf16 v[96:99], v[146:149], v[232:235], v[96:99]
	v_mfma_f32_16x16x32_bf16 v[124:127], v[132:135], v[190:193], v[124:127]
	v_mfma_f32_16x16x32_bf16 v[120:123], v[150:153], v[190:193], v[120:123]
	v_mfma_f32_16x16x32_bf16 v[116:119], v[132:135], v[198:201], v[116:119]
	v_mfma_f32_16x16x32_bf16 v[112:115], v[150:153], v[198:201], v[112:115]
	v_mfma_f32_16x16x32_bf16 v[108:111], v[132:135], v[228:231], v[108:111]
	v_mfma_f32_16x16x32_bf16 v[104:107], v[150:153], v[228:231], v[104:107]
	v_mfma_f32_16x16x32_bf16 v[100:103], v[132:135], v[236:239], v[100:103]
	v_mfma_f32_16x16x32_bf16 v[96:99], v[150:153], v[236:239], v[96:99]
	s_setprio 0
	s_setprio 1
	v_mfma_f32_16x16x32_bf16 v[64:67], v[170:173], v[186:189], v[64:67]
	v_mfma_f32_16x16x32_bf16 v[60:63], v[178:181], v[186:189], v[60:63]
	v_mfma_f32_16x16x32_bf16 v[52:55], v[170:173], v[194:197], v[52:55]
	v_mfma_f32_16x16x32_bf16 v[48:51], v[178:181], v[194:197], v[48:51]
	v_mfma_f32_16x16x32_bf16 v[44:47], v[170:173], v[202:205], v[44:47]
	v_mfma_f32_16x16x32_bf16 v[40:43], v[178:181], v[202:205], v[40:43]
	v_mfma_f32_16x16x32_bf16 v[36:39], v[170:173], v[232:235], v[36:39]
	v_mfma_f32_16x16x32_bf16 v[32:35], v[178:181], v[232:235], v[32:35]
	v_mfma_f32_16x16x32_bf16 v[64:67], v[174:177], v[190:193], v[64:67]
	v_mfma_f32_16x16x32_bf16 v[60:63], v[182:185], v[190:193], v[60:63]
	v_mfma_f32_16x16x32_bf16 v[52:55], v[174:177], v[198:201], v[52:55]
	v_mfma_f32_16x16x32_bf16 v[48:51], v[182:185], v[198:201], v[48:51]
	v_mfma_f32_16x16x32_bf16 v[44:47], v[174:177], v[228:231], v[44:47]
	v_mfma_f32_16x16x32_bf16 v[40:43], v[182:185], v[228:231], v[40:43]
	v_mfma_f32_16x16x32_bf16 v[36:39], v[174:177], v[236:239], v[36:39]
	v_mfma_f32_16x16x32_bf16 v[32:35], v[182:185], v[236:239], v[32:35]
	s_setprio 0
	s_barrier
	ds_read_b128 v[186:189], v159 offset:16384
	ds_read_b128 v[190:193], v159 offset:17408
	ds_read_b128 v[194:197], v159 offset:18432
	ds_read_b128 v[198:201], v159 offset:19456
	ds_read_b128 v[202:205], v159 offset:20480
	ds_read_b128 v[228:231], v159 offset:21504
	ds_read_b128 v[232:235], v159 offset:22528
	ds_read_b128 v[236:239], v159 offset:23552
	s_add_i32 s45, s45, s77
	s_mov_b32 m0, s45
	v_lshl_add_u64 v[154:155], s[20:21], 0, v[160:161]
	global_load_lds_dwordx4 v[154:155], off
	s_add_i32 m0, s45, 0x2000
	s_add_u32 s46, s20, 0x100000
	v_lshl_add_u64 v[166:167], s[20:21], 0, v[136:137]
	s_addc_u32 s47, s21, 0
	s_add_i32 s45, s48, s77
	global_load_lds_dwordx4 v[166:167], off
	v_lshl_add_u64 v[168:169], s[46:47], 0, v[160:161]
	s_mov_b32 m0, s45
	v_lshl_add_u64 v[206:207], s[22:23], 0, v[138:139]
	global_load_lds_dwordx4 v[168:169], off
	v_lshl_add_u64 v[168:169], s[46:47], 0, v[136:137]
	s_add_i32 m0, s45, 0x2000
	s_nop 0
	global_load_lds_dwordx4 v[168:169], off
	v_lshl_add_u64 v[168:169], s[22:23], 0, v[140:141]
	s_mov_b32 m0, s27
	s_nop 0
	global_load_lds_dwordx4 v[168:169], off
	s_mov_b32 m0, s28
	s_nop 0
	global_load_lds_dwordx4 v[206:207], off
	s_waitcnt vmcnt(8)
	s_waitcnt lgkmcnt(0)
	s_barrier
	s_setprio 1
	s_waitcnt lgkmcnt(0)
	v_mfma_f32_16x16x32_bf16 v[92:95], v[128:131], v[186:189], v[92:95]
	v_mfma_f32_16x16x32_bf16 v[88:91], v[146:149], v[186:189], v[88:91]
	v_mfma_f32_16x16x32_bf16 v[84:87], v[128:131], v[194:197], v[84:87]
	v_mfma_f32_16x16x32_bf16 v[80:83], v[146:149], v[194:197], v[80:83]
	v_mfma_f32_16x16x32_bf16 v[76:79], v[128:131], v[202:205], v[76:79]
	v_mfma_f32_16x16x32_bf16 v[72:75], v[146:149], v[202:205], v[72:75]
	v_mfma_f32_16x16x32_bf16 v[68:71], v[128:131], v[232:235], v[68:71]
	v_mfma_f32_16x16x32_bf16 v[56:59], v[146:149], v[232:235], v[56:59]
	v_mfma_f32_16x16x32_bf16 v[92:95], v[132:135], v[190:193], v[92:95]
	v_mfma_f32_16x16x32_bf16 v[88:91], v[150:153], v[190:193], v[88:91]
	v_mfma_f32_16x16x32_bf16 v[84:87], v[132:135], v[198:201], v[84:87]
	v_mfma_f32_16x16x32_bf16 v[80:83], v[150:153], v[198:201], v[80:83]
	v_mfma_f32_16x16x32_bf16 v[76:79], v[132:135], v[228:231], v[76:79]
	v_mfma_f32_16x16x32_bf16 v[72:75], v[150:153], v[228:231], v[72:75]
	v_mfma_f32_16x16x32_bf16 v[68:71], v[132:135], v[236:239], v[68:71]
	v_mfma_f32_16x16x32_bf16 v[56:59], v[150:153], v[236:239], v[56:59]
	s_setprio 0
	s_setprio 1
	v_mfma_f32_16x16x32_bf16 v[28:31], v[170:173], v[186:189], v[28:31]
	v_mfma_f32_16x16x32_bf16 v[24:27], v[178:181], v[186:189], v[24:27]
	v_mfma_f32_16x16x32_bf16 v[20:23], v[170:173], v[194:197], v[20:23]
	v_mfma_f32_16x16x32_bf16 v[16:19], v[178:181], v[194:197], v[16:19]
	v_mfma_f32_16x16x32_bf16 v[12:15], v[170:173], v[202:205], v[12:15]
	v_mfma_f32_16x16x32_bf16 v[8:11], v[178:181], v[202:205], v[8:11]
	v_mfma_f32_16x16x32_bf16 v[4:7], v[170:173], v[232:235], v[4:7]
	v_mfma_f32_16x16x32_bf16 v[0:3], v[178:181], v[232:235], v[0:3]
	v_mfma_f32_16x16x32_bf16 v[28:31], v[174:177], v[190:193], v[28:31]
	v_mfma_f32_16x16x32_bf16 v[24:27], v[182:185], v[190:193], v[24:27]
	v_mfma_f32_16x16x32_bf16 v[20:23], v[174:177], v[198:201], v[20:23]
	v_mfma_f32_16x16x32_bf16 v[16:19], v[182:185], v[198:201], v[16:19]
	v_mfma_f32_16x16x32_bf16 v[12:15], v[174:177], v[228:231], v[12:15]
	v_mfma_f32_16x16x32_bf16 v[8:11], v[182:185], v[228:231], v[8:11]
	v_mfma_f32_16x16x32_bf16 v[4:7], v[174:177], v[236:239], v[4:7]
	v_mfma_f32_16x16x32_bf16 v[0:3], v[182:185], v[236:239], v[0:3]
	s_setprio 0
	s_barrier
	s_add_i32 s45, 0, 0x18000
	s_add_i32 s46, 0, 0x1c000
	v_add_u32_e32 v150, s45, v157
	v_add_u32_e32 v182, s46, v157
	ds_read_b128 v[128:131], v150
	ds_read_b128 v[132:135], v150 offset:1024
	ds_read_b128 v[146:149], v150 offset:2048
	ds_read_b128 v[150:153], v150 offset:3072
	ds_read_b128 v[170:173], v182
	ds_read_b128 v[174:177], v182 offset:1024
	ds_read_b128 v[178:181], v182 offset:2048
	ds_read_b128 v[182:185], v182 offset:3072
	s_add_u32 s22, s22, 0x100000
	s_addc_u32 s23, s23, 0
	s_mov_b32 m0, s29
	v_lshl_add_u64 v[240:241], s[22:23], 0, v[140:141]
	ds_read_b128 v[186:189], v159 offset:32768
	ds_read_b128 v[190:193], v159 offset:33792
	ds_read_b128 v[194:197], v159 offset:34816
	ds_read_b128 v[198:201], v159 offset:35840
	ds_read_b128 v[202:205], v159 offset:36864
	ds_read_b128 v[228:231], v159 offset:37888
	ds_read_b128 v[232:235], v159 offset:38912
	ds_read_b128 v[236:239], v159 offset:39936
	global_load_lds_dwordx4 v[240:241], off
	v_lshl_add_u64 v[240:241], s[22:23], 0, v[138:139]
	s_mov_b32 m0, s30
	s_nop 0
	global_load_lds_dwordx4 v[240:241], off
	s_waitcnt vmcnt(8)
	s_waitcnt lgkmcnt(0)
	s_barrier
	s_setprio 1
	s_waitcnt lgkmcnt(0)
	v_mfma_f32_16x16x32_bf16 v[124:127], v[128:131], v[186:189], v[124:127]
	v_mfma_f32_16x16x32_bf16 v[120:123], v[146:149], v[186:189], v[120:123]
	v_mfma_f32_16x16x32_bf16 v[116:119], v[128:131], v[194:197], v[116:119]
	v_mfma_f32_16x16x32_bf16 v[112:115], v[146:149], v[194:197], v[112:115]
	v_mfma_f32_16x16x32_bf16 v[108:111], v[128:131], v[202:205], v[108:111]
	v_mfma_f32_16x16x32_bf16 v[104:107], v[146:149], v[202:205], v[104:107]
	v_mfma_f32_16x16x32_bf16 v[100:103], v[128:131], v[232:235], v[100:103]
	v_mfma_f32_16x16x32_bf16 v[96:99], v[146:149], v[232:235], v[96:99]
	v_mfma_f32_16x16x32_bf16 v[124:127], v[132:135], v[190:193], v[124:127]
	v_mfma_f32_16x16x32_bf16 v[120:123], v[150:153], v[190:193], v[120:123]
	v_mfma_f32_16x16x32_bf16 v[116:119], v[132:135], v[198:201], v[116:119]
	v_mfma_f32_16x16x32_bf16 v[112:115], v[150:153], v[198:201], v[112:115]
	v_mfma_f32_16x16x32_bf16 v[108:111], v[132:135], v[228:231], v[108:111]
	v_mfma_f32_16x16x32_bf16 v[104:107], v[150:153], v[228:231], v[104:107]
	v_mfma_f32_16x16x32_bf16 v[100:103], v[132:135], v[236:239], v[100:103]
	v_mfma_f32_16x16x32_bf16 v[96:99], v[150:153], v[236:239], v[96:99]
	s_setprio 0
	s_setprio 1
	v_mfma_f32_16x16x32_bf16 v[64:67], v[170:173], v[186:189], v[64:67]
	v_mfma_f32_16x16x32_bf16 v[60:63], v[178:181], v[186:189], v[60:63]
	v_mfma_f32_16x16x32_bf16 v[52:55], v[170:173], v[194:197], v[52:55]
	v_mfma_f32_16x16x32_bf16 v[48:51], v[178:181], v[194:197], v[48:51]
	v_mfma_f32_16x16x32_bf16 v[44:47], v[170:173], v[202:205], v[44:47]
	v_mfma_f32_16x16x32_bf16 v[40:43], v[178:181], v[202:205], v[40:43]
	v_mfma_f32_16x16x32_bf16 v[36:39], v[170:173], v[232:235], v[36:39]
	v_mfma_f32_16x16x32_bf16 v[32:35], v[178:181], v[232:235], v[32:35]
	v_mfma_f32_16x16x32_bf16 v[64:67], v[174:177], v[190:193], v[64:67]
	v_mfma_f32_16x16x32_bf16 v[60:63], v[182:185], v[190:193], v[60:63]
	v_mfma_f32_16x16x32_bf16 v[52:55], v[174:177], v[198:201], v[52:55]
	v_mfma_f32_16x16x32_bf16 v[48:51], v[182:185], v[198:201], v[48:51]
	v_mfma_f32_16x16x32_bf16 v[44:47], v[174:177], v[228:231], v[44:47]
	v_mfma_f32_16x16x32_bf16 v[40:43], v[182:185], v[228:231], v[40:43]
	v_mfma_f32_16x16x32_bf16 v[36:39], v[174:177], v[236:239], v[36:39]
	v_mfma_f32_16x16x32_bf16 v[32:35], v[182:185], v[236:239], v[32:35]
	s_setprio 0
	s_barrier
	ds_read_b128 v[186:189], v159 offset:49152
	ds_read_b128 v[190:193], v159 offset:50176
	ds_read_b128 v[194:197], v159 offset:51200
	ds_read_b128 v[198:201], v159 offset:52224
	ds_read_b128 v[202:205], v159 offset:53248
	ds_read_b128 v[228:231], v159 offset:54272
	ds_read_b128 v[232:235], v159 offset:55296
	ds_read_b128 v[236:239], v159 offset:56320
	s_add_i32 s22, s45, s77
	s_mov_b32 m0, s22
	v_lshl_add_u64 v[154:155], v[154:155], 0, s[96:97]
	global_load_lds_dwordx4 v[154:155], off
	s_add_i32 m0, s22, 0x2000
	s_add_u32 s20, s20, 0x100080
	v_lshl_add_u64 v[154:155], v[166:167], 0, s[96:97]
	s_addc_u32 s21, s21, 0
	s_add_i32 s22, s46, s77
	global_load_lds_dwordx4 v[154:155], off
	v_lshl_add_u64 v[154:155], s[20:21], 0, v[160:161]
	s_mov_b32 m0, s22
	s_nop 0
	global_load_lds_dwordx4 v[154:155], off
	v_lshl_add_u64 v[154:155], s[20:21], 0, v[136:137]
	s_add_i32 m0, s22, 0x2000
	s_nop 0
	global_load_lds_dwordx4 v[154:155], off
	v_lshl_add_u64 v[154:155], v[168:169], 0, s[96:97]
	s_mov_b32 m0, s35
	s_nop 0
	global_load_lds_dwordx4 v[154:155], off
	v_lshl_add_u64 v[154:155], v[206:207], 0, s[96:97]
	s_mov_b32 m0, s36
	s_nop 0
	global_load_lds_dwordx4 v[154:155], off
	s_waitcnt vmcnt(8)
	s_waitcnt lgkmcnt(0)
	s_barrier
	s_setprio 1
	s_waitcnt lgkmcnt(0)
	v_mfma_f32_16x16x32_bf16 v[92:95], v[128:131], v[186:189], v[92:95]
	v_mfma_f32_16x16x32_bf16 v[88:91], v[146:149], v[186:189], v[88:91]
	v_mfma_f32_16x16x32_bf16 v[84:87], v[128:131], v[194:197], v[84:87]
	v_mfma_f32_16x16x32_bf16 v[80:83], v[146:149], v[194:197], v[80:83]
	v_mfma_f32_16x16x32_bf16 v[76:79], v[128:131], v[202:205], v[76:79]
	v_mfma_f32_16x16x32_bf16 v[72:75], v[146:149], v[202:205], v[72:75]
	v_mfma_f32_16x16x32_bf16 v[68:71], v[128:131], v[232:235], v[68:71]
	v_mfma_f32_16x16x32_bf16 v[56:59], v[146:149], v[232:235], v[56:59]
	v_mfma_f32_16x16x32_bf16 v[92:95], v[132:135], v[190:193], v[92:95]
	v_mfma_f32_16x16x32_bf16 v[88:91], v[150:153], v[190:193], v[88:91]
	v_mfma_f32_16x16x32_bf16 v[84:87], v[132:135], v[198:201], v[84:87]
	v_mfma_f32_16x16x32_bf16 v[80:83], v[150:153], v[198:201], v[80:83]
	v_mfma_f32_16x16x32_bf16 v[76:79], v[132:135], v[228:231], v[76:79]
	v_mfma_f32_16x16x32_bf16 v[72:75], v[150:153], v[228:231], v[72:75]
	v_mfma_f32_16x16x32_bf16 v[68:71], v[132:135], v[236:239], v[68:71]
	v_mfma_f32_16x16x32_bf16 v[56:59], v[150:153], v[236:239], v[56:59]
	s_setprio 0
	s_setprio 1
	v_mfma_f32_16x16x32_bf16 v[28:31], v[170:173], v[186:189], v[28:31]
	v_mfma_f32_16x16x32_bf16 v[24:27], v[178:181], v[186:189], v[24:27]
	v_mfma_f32_16x16x32_bf16 v[20:23], v[170:173], v[194:197], v[20:23]
	v_mfma_f32_16x16x32_bf16 v[16:19], v[178:181], v[194:197], v[16:19]
	v_mfma_f32_16x16x32_bf16 v[12:15], v[170:173], v[202:205], v[12:15]
	v_mfma_f32_16x16x32_bf16 v[8:11], v[178:181], v[202:205], v[8:11]
	v_mfma_f32_16x16x32_bf16 v[4:7], v[170:173], v[232:235], v[4:7]
	v_mfma_f32_16x16x32_bf16 v[0:3], v[178:181], v[232:235], v[0:3]
	v_mfma_f32_16x16x32_bf16 v[28:31], v[174:177], v[190:193], v[28:31]
	v_mfma_f32_16x16x32_bf16 v[24:27], v[182:185], v[190:193], v[24:27]
	v_mfma_f32_16x16x32_bf16 v[20:23], v[174:177], v[198:201], v[20:23]
	v_mfma_f32_16x16x32_bf16 v[16:19], v[182:185], v[198:201], v[16:19]
	v_mfma_f32_16x16x32_bf16 v[12:15], v[174:177], v[228:231], v[12:15]
	v_mfma_f32_16x16x32_bf16 v[8:11], v[182:185], v[228:231], v[8:11]
	v_mfma_f32_16x16x32_bf16 v[4:7], v[174:177], v[236:239], v[4:7]
	v_mfma_f32_16x16x32_bf16 v[0:3], v[182:185], v[236:239], v[0:3]
	s_setprio 0
	s_add_i32 s44, s44, 2
	s_add_u32 s42, s42, 0x100
	s_addc_u32 s43, s43, 0
	s_add_u32 s18, s18, 0x100
	s_addc_u32 s19, s19, 0
	s_cmp_gt_u32 s44, 61
	s_barrier
	s_cbranch_scc0 .LBB0_554
	v_readlane_b32 s18, v253, 23
	v_readlane_b32 s19, v253, 24
	s_and_b64 vcc, exec, s[18:19]
	s_cbranch_vccz .LBB0_557
	s_barrier
